# GEMM K loops: m0 set ahead of the DMA address add so the add fills the m0 hazard slot (40 s_nop removed)
# baseline (speedup 1.0000x reference)
; #define PG8_STAGE(bufoff, gbase, voff) do { _Pragma("unroll") for (int _i = 0; _i < 2; ++_i) \
;         __builtin_amdgcn_global_load_lds((const unsigned*)((const char*)(gbase) + (voff)[_i]), (LAS unsigned*)(lds + (bufoff) + ldsw + _i * 8192), 16, 0, 0); } while (0)
; #define PG8_LDA(dst, b, h) do { _Pragma("unroll") for (int m = 0; m < 4; ++m) _Pragma("unroll") for (int k = 0; k < 2; ++k) dst[m][k] = *(const LAS h16x8*)(lds + PG8_SA(b, h) + aoff + m * 2048 + k * 1024); } while (0)
; #define PG8_LDB(dst, b, h) do { _Pragma("unroll") for (int n = 0; n < 2; ++n) _Pragma("unroll") for (int k = 0; k < 2; ++k) dst[n][k] = *(const LAS h16x8*)(lds + PG8_SB(b, h) + boff + n * 2048 + k * 1024); } while (0)
; #define PG8_MMA(ai, bj, At, Bt) do { __builtin_amdgcn_s_setprio(1); _Pragma("unroll") for (int m = 0; m < 4; ++m) _Pragma("unroll") for (int n = 0; n < 2; ++n) _Pragma("unroll") for (int k = 0; k < 2; ++k) \
;         acc[ai][bj][m][n] = __builtin_amdgcn_mfma_f32_16x16x32_f16(Bt[n][k], At[m][k], acc[ai][bj][m][n], 0, 0, 0); __builtin_amdgcn_s_setprio(0); } while (0)
; #define PG8_WAIT_V(n) asm volatile("s_waitcnt vmcnt(" #n ")" ::: "memory")
; #define PG8_WAIT_L(n) asm volatile("s_waitcnt lgkmcnt(" #n ")" ::: "memory")
; #define PG8_BAR __builtin_amdgcn_s_barrier()
; #define PG8_SCHED __builtin_amdgcn_sched_barrier(0)
; template <class Epi>
; __device__ __forceinline__ void gemm_phase(LAS unsigned char* lds, const Gemm g, const StaticOrder& S, const Epi& E) {
;     ...
;             PG8_LDB(B0, 0, 0); PG8_SCHED; PG8_LDA(At, 0, 0); PG8_STAGE(PG8_SA(1, 1), a1 + hstep, voffA);
;             PG8_WAIT_L(8); PG8_BAR; PG8_WAIT_L(0); PG8_MMA(0, 0, At, B0); PG8_BAR; PG8_SCHED;
;             PG8_LDB(B1, 0, 1); PG8_STAGE(PG8_SB(0, 0), b2, voffB);
;             PG8_BAR; PG8_WAIT_L(0); PG8_MMA(0, 1, At, B1); PG8_BAR;
;             PG8_LDA(At, 0, 1); PG8_STAGE(PG8_SA(0, 0), a2, voffA);
;             PG8_BAR; PG8_WAIT_L(0); PG8_MMA(1, 0, At, B0); PG8_BAR; PG8_SCHED;
;             PG8_STAGE(PG8_SB(0, 1), b2 + hstep, voffB);
;             PG8_WAIT_V(6); PG8_BAR; PG8_MMA(1, 1, At, B1); PG8_BAR;
.LBB0_195:
	ds_read_b128 v[148:151], v159
	ds_read_b128 v[164:167], v159 offset:1024
	ds_read_b128 v[168:171], v159 offset:2048
	ds_read_b128 v[172:175], v159 offset:3072
	s_add_u32 s34, s80, 0xfffc0080
	s_addc_u32 s35, s81, -1
	s_cmp_eq_u32 s15, 12
	s_cselect_b32 s85, s49, s35
	s_cselect_b32 s84, s79, s34
	s_cselect_b32 s83, s47, s14
	s_cselect_b32 s82, vcc_lo, vcc_hi
	s_waitcnt lgkmcnt(0)
	v_lshl_add_u64 v[152:153], s[80:81], 0, v[140:141]
	s_add_i32 m0, s77, 0xc000
	ds_read_b128 v[176:179], v160
	ds_read_b128 v[180:183], v160 offset:1024
	ds_read_b128 v[184:187], v160 offset:2048
	ds_read_b128 v[188:191], v160 offset:3072
	ds_read_b128 v[192:195], v160 offset:4096
	ds_read_b128 v[196:199], v160 offset:5120
	ds_read_b128 v[200:203], v160 offset:6144
	ds_read_b128 v[204:207], v160 offset:7168
	global_load_lds_dwordx4 v[152:153], off
	s_add_i32 m0, s77, 0xe000
	v_lshl_add_u64 v[152:153], s[80:81], 0, v[142:143]
	global_load_lds_dwordx4 v[152:153], off
	s_waitcnt lgkmcnt(8)
	s_barrier
	s_waitcnt lgkmcnt(0)
	s_waitcnt lgkmcnt(0)
	v_mfma_f32_16x16x32_f16 v[124:127], v[148:151], v[176:179], v[124:127]
	v_mfma_f32_16x16x32_f16 v[120:123], v[168:171], v[176:179], v[120:123]
	v_mfma_f32_16x16x32_f16 v[108:111], v[148:151], v[184:187], v[108:111]
	v_mfma_f32_16x16x32_f16 v[104:107], v[168:171], v[184:187], v[104:107]
	v_mfma_f32_16x16x32_f16 v[92:95], v[148:151], v[192:195], v[92:95]
	v_mfma_f32_16x16x32_f16 v[88:91], v[168:171], v[192:195], v[88:91]
	v_mfma_f32_16x16x32_f16 v[76:79], v[148:151], v[200:203], v[76:79]
	v_mfma_f32_16x16x32_f16 v[72:75], v[168:171], v[200:203], v[72:75]
	v_mfma_f32_16x16x32_f16 v[124:127], v[164:167], v[180:183], v[124:127]
	v_mfma_f32_16x16x32_f16 v[120:123], v[172:175], v[180:183], v[120:123]
	v_mfma_f32_16x16x32_f16 v[108:111], v[164:167], v[188:191], v[108:111]
	v_mfma_f32_16x16x32_f16 v[104:107], v[172:175], v[188:191], v[104:107]
	v_mfma_f32_16x16x32_f16 v[92:95], v[164:167], v[196:199], v[92:95]
	v_mfma_f32_16x16x32_f16 v[88:91], v[172:175], v[196:199], v[88:91]
	v_mfma_f32_16x16x32_f16 v[76:79], v[164:167], v[204:207], v[76:79]
	v_mfma_f32_16x16x32_f16 v[72:75], v[172:175], v[204:207], v[72:75]
	s_barrier
	s_add_i32 s34, s97, s87
	v_lshl_add_u64 v[152:153], s[82:83], 0, v[132:133]
	s_mov_b32 m0, s34
	ds_read_b128 v[208:211], v161
	ds_read_b128 v[212:215], v161 offset:1024
	ds_read_b128 v[216:219], v161 offset:2048
	ds_read_b128 v[220:223], v161 offset:3072
	global_load_lds_dwordx4 v[152:153], off
	s_add_i32 m0, s34, 0x2000
	v_lshl_add_u64 v[224:225], s[82:83], 0, v[136:137]
	global_load_lds_dwordx4 v[224:225], off
	s_barrier
	s_waitcnt lgkmcnt(0)
	s_waitcnt lgkmcnt(0)
	v_mfma_f32_16x16x32_f16 v[116:119], v[208:211], v[176:179], v[116:119]
	v_mfma_f32_16x16x32_f16 v[112:115], v[216:219], v[176:179], v[112:115]
	v_mfma_f32_16x16x32_f16 v[100:103], v[208:211], v[184:187], v[100:103]
	v_mfma_f32_16x16x32_f16 v[96:99], v[216:219], v[184:187], v[96:99]
	v_mfma_f32_16x16x32_f16 v[84:87], v[208:211], v[192:195], v[84:87]
	v_mfma_f32_16x16x32_f16 v[80:83], v[216:219], v[192:195], v[80:83]
	v_mfma_f32_16x16x32_f16 v[68:71], v[208:211], v[200:203], v[68:71]
	v_mfma_f32_16x16x32_f16 v[64:67], v[216:219], v[200:203], v[64:67]
	v_mfma_f32_16x16x32_f16 v[116:119], v[212:215], v[180:183], v[116:119]
	v_mfma_f32_16x16x32_f16 v[112:115], v[220:223], v[180:183], v[112:115]
	v_mfma_f32_16x16x32_f16 v[100:103], v[212:215], v[188:191], v[100:103]
	v_mfma_f32_16x16x32_f16 v[96:99], v[220:223], v[188:191], v[96:99]
	v_mfma_f32_16x16x32_f16 v[84:87], v[212:215], v[196:199], v[84:87]
	v_mfma_f32_16x16x32_f16 v[80:83], v[220:223], v[196:199], v[80:83]
	v_mfma_f32_16x16x32_f16 v[68:71], v[212:215], v[204:207], v[68:71]
	v_mfma_f32_16x16x32_f16 v[64:67], v[220:223], v[204:207], v[64:67]
	s_mov_b32 m0, s77
	v_lshl_add_u64 v[226:227], s[84:85], 0, v[128:129]
	s_barrier
	ds_read_b128 v[176:179], v160 offset:16384
	ds_read_b128 v[180:183], v160 offset:17408
	ds_read_b128 v[184:187], v160 offset:18432
	ds_read_b128 v[188:191], v160 offset:19456
	ds_read_b128 v[192:195], v160 offset:20480
	ds_read_b128 v[196:199], v160 offset:21504
	ds_read_b128 v[200:203], v160 offset:22528
	ds_read_b128 v[204:207], v160 offset:23552
	global_load_lds_dwordx4 v[226:227], off
	s_mov_b32 m0, s88
	v_lshl_add_u64 v[228:229], s[84:85], 0, v[134:135]
	global_load_lds_dwordx4 v[228:229], off
	s_barrier
	s_waitcnt lgkmcnt(0)
	s_waitcnt lgkmcnt(0)
	v_mfma_f32_16x16x32_f16 v[60:63], v[148:151], v[176:179], v[60:63]
	v_mfma_f32_16x16x32_f16 v[56:59], v[168:171], v[176:179], v[56:59]
	v_mfma_f32_16x16x32_f16 v[44:47], v[148:151], v[184:187], v[44:47]
	v_mfma_f32_16x16x32_f16 v[40:43], v[168:171], v[184:187], v[40:43]
	v_mfma_f32_16x16x32_f16 v[28:31], v[148:151], v[192:195], v[28:31]
	v_mfma_f32_16x16x32_f16 v[24:27], v[168:171], v[192:195], v[24:27]
	v_mfma_f32_16x16x32_f16 v[12:15], v[148:151], v[200:203], v[12:15]
	v_mfma_f32_16x16x32_f16 v[8:11], v[168:171], v[200:203], v[8:11]
	v_mfma_f32_16x16x32_f16 v[60:63], v[164:167], v[180:183], v[60:63]
	v_mfma_f32_16x16x32_f16 v[56:59], v[172:175], v[180:183], v[56:59]
	v_mfma_f32_16x16x32_f16 v[44:47], v[164:167], v[188:191], v[44:47]
	v_mfma_f32_16x16x32_f16 v[40:43], v[172:175], v[188:191], v[40:43]
	v_mfma_f32_16x16x32_f16 v[28:31], v[164:167], v[196:199], v[28:31]
	v_mfma_f32_16x16x32_f16 v[24:27], v[172:175], v[196:199], v[24:27]
	v_mfma_f32_16x16x32_f16 v[12:15], v[164:167], v[204:207], v[12:15]
	v_mfma_f32_16x16x32_f16 v[8:11], v[172:175], v[204:207], v[8:11]
	s_barrier
; #define PG8_STAGE(bufoff, gbase, voff) do { _Pragma("unroll") for (int _i = 0; _i < 2; ++_i) \
;         __builtin_amdgcn_global_load_lds((const unsigned*)((const char*)(gbase) + (voff)[_i]), (LAS unsigned*)(lds + (bufoff) + ldsw + _i * 8192), 16, 0, 0); } while (0)
; #define PG8_LDA(dst, b, h) do { _Pragma("unroll") for (int m = 0; m < 4; ++m) _Pragma("unroll") for (int k = 0; k < 2; ++k) dst[m][k] = *(const LAS h16x8*)(lds + PG8_SA(b, h) + aoff + m * 2048 + k * 1024); } while (0)
; #define PG8_LDB(dst, b, h) do { _Pragma("unroll") for (int n = 0; n < 2; ++n) _Pragma("unroll") for (int k = 0; k < 2; ++k) dst[n][k] = *(const LAS h16x8*)(lds + PG8_SB(b, h) + boff + n * 2048 + k * 1024); } while (0)
; #define PG8_MMA(ai, bj, At, Bt) do { __builtin_amdgcn_s_setprio(1); _Pragma("unroll") for (int m = 0; m < 4; ++m) _Pragma("unroll") for (int n = 0; n < 2; ++n) _Pragma("unroll") for (int k = 0; k < 2; ++k) \
;         acc[ai][bj][m][n] = __builtin_amdgcn_mfma_f32_16x16x32_f16(Bt[n][k], At[m][k], acc[ai][bj][m][n], 0, 0, 0); __builtin_amdgcn_s_setprio(0); } while (0)
; #define PG8_WAIT_V(n) asm volatile("s_waitcnt vmcnt(" #n ")" ::: "memory")
; #define PG8_WAIT_L(n) asm volatile("s_waitcnt lgkmcnt(" #n ")" ::: "memory")
; #define PG8_BAR __builtin_amdgcn_s_barrier()
; #define PG8_SCHED __builtin_amdgcn_sched_barrier(0)
; template <class Epi>
; __device__ __forceinline__ void gemm_phase(LAS unsigned char* lds, const Gemm g, const StaticOrder& S, const Epi& E) {
;     ...
;             PG8_STAGE(PG8_SB(0, 1), b2 + hstep, voffB);
;             PG8_WAIT_V(6); PG8_BAR; PG8_MMA(1, 1, At, B1); PG8_BAR;
;             PG8_LDB(B0, 1, 0); PG8_SCHED; PG8_LDA(At, 1, 0); PG8_STAGE(PG8_SA(0, 1), a2 + hstep, voffA);
;             PG8_WAIT_L(8); PG8_BAR; PG8_WAIT_L(0); PG8_MMA(0, 0, At, B0); PG8_BAR; PG8_SCHED;
;             PG8_LDB(B1, 1, 1); PG8_STAGE(PG8_SB(1, 0), b3, voffB);
;             PG8_BAR; PG8_WAIT_L(0); PG8_MMA(0, 1, At, B1); PG8_BAR;
;             PG8_LDA(At, 1, 1); PG8_STAGE(PG8_SA(1, 0), a3, voffA);
;             PG8_BAR; PG8_WAIT_L(0); PG8_MMA(1, 0, At, B0); PG8_BAR; PG8_SCHED;
	s_add_u32 s34, s82, 0x40000
	s_addc_u32 s35, s83, 0
	s_add_i32 s86, s33, s87
	s_mov_b32 m0, s86
	v_lshl_add_u64 v[148:149], s[34:35], 0, v[132:133]
	global_load_lds_dwordx4 v[148:149], off
	s_add_i32 m0, s86, 0x2000
	v_lshl_add_u64 v[148:149], s[34:35], 0, v[136:137]
	global_load_lds_dwordx4 v[148:149], off
	s_waitcnt vmcnt(6)
	s_barrier
	v_mfma_f32_16x16x32_f16 v[52:55], v[208:211], v[176:179], v[52:55]
	v_mfma_f32_16x16x32_f16 v[48:51], v[216:219], v[176:179], v[48:51]
	v_mfma_f32_16x16x32_f16 v[36:39], v[208:211], v[184:187], v[36:39]
	v_mfma_f32_16x16x32_f16 v[32:35], v[216:219], v[184:187], v[32:35]
	v_mfma_f32_16x16x32_f16 v[20:23], v[208:211], v[192:195], v[20:23]
	v_mfma_f32_16x16x32_f16 v[16:19], v[216:219], v[192:195], v[16:19]
	v_mfma_f32_16x16x32_f16 v[4:7], v[208:211], v[200:203], v[4:7]
	v_mfma_f32_16x16x32_f16 v[0:3], v[216:219], v[200:203], v[0:3]
	v_mfma_f32_16x16x32_f16 v[52:55], v[212:215], v[180:183], v[52:55]
	v_mfma_f32_16x16x32_f16 v[48:51], v[220:223], v[180:183], v[48:51]
	v_mfma_f32_16x16x32_f16 v[36:39], v[212:215], v[188:191], v[36:39]
	v_mfma_f32_16x16x32_f16 v[32:35], v[220:223], v[188:191], v[32:35]
	v_mfma_f32_16x16x32_f16 v[20:23], v[212:215], v[196:199], v[20:23]
	v_mfma_f32_16x16x32_f16 v[16:19], v[220:223], v[196:199], v[16:19]
	v_mfma_f32_16x16x32_f16 v[4:7], v[212:215], v[204:207], v[4:7]
	v_mfma_f32_16x16x32_f16 v[0:3], v[220:223], v[204:207], v[0:3]
	s_add_i32 s86, 0, 0x18000
	v_add_u32_e32 v138, s86, v155
	s_barrier
	ds_read_b128 v[148:151], v138
	ds_read_b128 v[164:167], v138 offset:1024
	ds_read_b128 v[168:171], v138 offset:2048
	ds_read_b128 v[172:175], v138 offset:3072
	s_add_u32 s34, s84, 0x40000
	s_addc_u32 s35, s85, 0
	s_mov_b32 m0, s89
	v_lshl_add_u64 v[208:209], s[34:35], 0, v[128:129]
	ds_read_b128 v[176:179], v160 offset:32768
	ds_read_b128 v[180:183], v160 offset:33792
	ds_read_b128 v[184:187], v160 offset:34816
	ds_read_b128 v[188:191], v160 offset:35840
	ds_read_b128 v[192:195], v160 offset:36864
	ds_read_b128 v[196:199], v160 offset:37888
	ds_read_b128 v[200:203], v160 offset:38912
	ds_read_b128 v[204:207], v160 offset:39936
	global_load_lds_dwordx4 v[208:209], off
	s_mov_b32 m0, s90
	v_lshl_add_u64 v[208:209], s[34:35], 0, v[134:135]
	global_load_lds_dwordx4 v[208:209], off
	s_waitcnt lgkmcnt(8)
	s_barrier
	s_waitcnt lgkmcnt(0)
	s_waitcnt lgkmcnt(0)
	v_mfma_f32_16x16x32_f16 v[124:127], v[148:151], v[176:179], v[124:127]
	v_mfma_f32_16x16x32_f16 v[120:123], v[168:171], v[176:179], v[120:123]
	v_mfma_f32_16x16x32_f16 v[108:111], v[148:151], v[184:187], v[108:111]
	v_mfma_f32_16x16x32_f16 v[104:107], v[168:171], v[184:187], v[104:107]
	v_mfma_f32_16x16x32_f16 v[92:95], v[148:151], v[192:195], v[92:95]
	v_mfma_f32_16x16x32_f16 v[88:91], v[168:171], v[192:195], v[88:91]
	v_mfma_f32_16x16x32_f16 v[76:79], v[148:151], v[200:203], v[76:79]
	v_mfma_f32_16x16x32_f16 v[72:75], v[168:171], v[200:203], v[72:75]
	v_mfma_f32_16x16x32_f16 v[124:127], v[164:167], v[180:183], v[124:127]
	v_mfma_f32_16x16x32_f16 v[120:123], v[172:175], v[180:183], v[120:123]
	v_mfma_f32_16x16x32_f16 v[108:111], v[164:167], v[188:191], v[108:111]
	v_mfma_f32_16x16x32_f16 v[104:107], v[172:175], v[188:191], v[104:107]
	v_mfma_f32_16x16x32_f16 v[92:95], v[164:167], v[196:199], v[92:95]
	v_mfma_f32_16x16x32_f16 v[88:91], v[172:175], v[196:199], v[88:91]
	v_mfma_f32_16x16x32_f16 v[76:79], v[164:167], v[204:207], v[76:79]
	v_mfma_f32_16x16x32_f16 v[72:75], v[172:175], v[204:207], v[72:75]
	s_barrier
	s_add_i32 s84, 0, 0x1c000
	s_add_i32 s34, s86, s87
	v_add_u32_e32 v138, s84, v155
	v_lshl_add_u64 v[152:153], v[152:153], 0, s[28:29]
	s_mov_b32 m0, s34
	ds_read_b128 v[208:211], v138
	ds_read_b128 v[212:215], v138 offset:1024
	ds_read_b128 v[216:219], v138 offset:2048
	ds_read_b128 v[220:223], v138 offset:3072
	global_load_lds_dwordx4 v[152:153], off
	s_add_i32 m0, s34, 0x2000
	v_lshl_add_u64 v[152:153], v[224:225], 0, s[28:29]
	global_load_lds_dwordx4 v[152:153], off
	s_barrier
	s_waitcnt lgkmcnt(0)
	s_waitcnt lgkmcnt(0)
	v_mfma_f32_16x16x32_f16 v[116:119], v[208:211], v[176:179], v[116:119]
	v_mfma_f32_16x16x32_f16 v[112:115], v[216:219], v[176:179], v[112:115]
	v_mfma_f32_16x16x32_f16 v[100:103], v[208:211], v[184:187], v[100:103]
	v_mfma_f32_16x16x32_f16 v[96:99], v[216:219], v[184:187], v[96:99]
	v_mfma_f32_16x16x32_f16 v[84:87], v[208:211], v[192:195], v[84:87]
	v_mfma_f32_16x16x32_f16 v[80:83], v[216:219], v[192:195], v[80:83]
	v_mfma_f32_16x16x32_f16 v[68:71], v[208:211], v[200:203], v[68:71]
	v_mfma_f32_16x16x32_f16 v[64:67], v[216:219], v[200:203], v[64:67]
	v_mfma_f32_16x16x32_f16 v[116:119], v[212:215], v[180:183], v[116:119]
	v_mfma_f32_16x16x32_f16 v[112:115], v[220:223], v[180:183], v[112:115]
	v_mfma_f32_16x16x32_f16 v[100:103], v[212:215], v[188:191], v[100:103]
	v_mfma_f32_16x16x32_f16 v[96:99], v[220:223], v[188:191], v[96:99]
	v_mfma_f32_16x16x32_f16 v[84:87], v[212:215], v[196:199], v[84:87]
	v_mfma_f32_16x16x32_f16 v[80:83], v[220:223], v[196:199], v[80:83]
	v_mfma_f32_16x16x32_f16 v[68:71], v[212:215], v[204:207], v[68:71]
	v_mfma_f32_16x16x32_f16 v[64:67], v[220:223], v[204:207], v[64:67]
	s_mov_b32 m0, s94
	v_lshl_add_u64 v[152:153], v[226:227], 0, s[28:29]
	s_barrier
	ds_read_b128 v[176:179], v160 offset:49152
	ds_read_b128 v[180:183], v160 offset:50176
	ds_read_b128 v[184:187], v160 offset:51200
	ds_read_b128 v[188:191], v160 offset:52224
	ds_read_b128 v[192:195], v160 offset:53248
	ds_read_b128 v[196:199], v160 offset:54272
	ds_read_b128 v[200:203], v160 offset:55296
	ds_read_b128 v[204:207], v160 offset:56320
	global_load_lds_dwordx4 v[152:153], off
	s_mov_b32 m0, s95
	v_lshl_add_u64 v[152:153], v[228:229], 0, s[28:29]
	global_load_lds_dwordx4 v[152:153], off
	s_barrier
; #define PG8_STAGE(bufoff, gbase, voff) do { _Pragma("unroll") for (int _i = 0; _i < 2; ++_i) \
;         __builtin_amdgcn_global_load_lds((const unsigned*)((const char*)(gbase) + (voff)[_i]), (LAS unsigned*)(lds + (bufoff) + ldsw + _i * 8192), 16, 0, 0); } while (0)
; #define PG8_MMA(ai, bj, At, Bt) do { __builtin_amdgcn_s_setprio(1); _Pragma("unroll") for (int m = 0; m < 4; ++m) _Pragma("unroll") for (int n = 0; n < 2; ++n) _Pragma("unroll") for (int k = 0; k < 2; ++k) \
;         acc[ai][bj][m][n] = __builtin_amdgcn_mfma_f32_16x16x32_f16(Bt[n][k], At[m][k], acc[ai][bj][m][n], 0, 0, 0); __builtin_amdgcn_s_setprio(0); } while (0)
; #define PG8_WAIT_V(n) asm volatile("s_waitcnt vmcnt(" #n ")" ::: "memory")
; #define PG8_WAIT_L(n) asm volatile("s_waitcnt lgkmcnt(" #n ")" ::: "memory")
; #define PG8_BAR __builtin_amdgcn_s_barrier()
; #define PG8_SCHED __builtin_amdgcn_sched_barrier(0)
; template <class Epi>
; __device__ __forceinline__ void gemm_phase(LAS unsigned char* lds, const Gemm g, const StaticOrder& S, const Epi& E) {
;     ...
;             PG8_BAR; PG8_WAIT_L(0); PG8_MMA(1, 0, At, B0); PG8_BAR; PG8_SCHED;
;             PG8_STAGE(PG8_SB(1, 1), b3 + hstep, voffB);
;             PG8_WAIT_V(6); PG8_BAR; PG8_MMA(1, 1, At, B1); PG8_BAR;
;     __device__ __forceinline__ void operator()(const f32x4 (&acc)[2][2][4][2], const pg8::Unit& u, int wr, int wc, int fr, int fq) const {
;     ...
;                 for (int m = 0; m < 4; ++m) { const size_t r = (size_t)(row0 + ai * 128 + m * 16); float s1 = 0.f, s2 = 0.f;
; #pragma unroll
;                     for (int bj = 0; bj < 2; ++bj) { const int ch = 256 * (T - 24) + 128 * bj + 32 * wc + 8 * fq; h16x8 o;
; #pragma unroll
;                         for (int n = 0; n < 2; ++n) { const f32x4 v = acc[ai][bj][m][n];
; #pragma unroll
;                             for (int e = 0; e < 4; ++e) { o[4 * n + e] = (h16)v[e]; const float f = (float)o[4 * n + e]; s1 += f; s2 += f * f; } }
;                         *(h16x8*)(V + r * 1024 + ch) = o; }
;                     s1 += __shfl_xor(s1, 16); s2 += __shfl_xor(s2, 16); s1 += __shfl_xor(s1, 32); s2 += __shfl_xor(s2, 32);
;                     if (fq == 0) { atomicAdd(st + 2 * r, s1); atomicAdd(st + 2 * r + 1, s2); } }
	s_waitcnt lgkmcnt(0)
	s_waitcnt lgkmcnt(0)
	v_mfma_f32_16x16x32_f16 v[60:63], v[148:151], v[176:179], v[60:63]
	v_mfma_f32_16x16x32_f16 v[56:59], v[168:171], v[176:179], v[56:59]
	v_mfma_f32_16x16x32_f16 v[44:47], v[148:151], v[184:187], v[44:47]
	v_mfma_f32_16x16x32_f16 v[40:43], v[168:171], v[184:187], v[40:43]
	v_mfma_f32_16x16x32_f16 v[28:31], v[148:151], v[192:195], v[28:31]
	v_mfma_f32_16x16x32_f16 v[24:27], v[168:171], v[192:195], v[24:27]
	v_mfma_f32_16x16x32_f16 v[12:15], v[148:151], v[200:203], v[12:15]
	v_mfma_f32_16x16x32_f16 v[8:11], v[168:171], v[200:203], v[8:11]
	v_mfma_f32_16x16x32_f16 v[60:63], v[164:167], v[180:183], v[60:63]
	v_mfma_f32_16x16x32_f16 v[56:59], v[172:175], v[180:183], v[56:59]
	v_mfma_f32_16x16x32_f16 v[44:47], v[164:167], v[188:191], v[44:47]
	v_mfma_f32_16x16x32_f16 v[40:43], v[172:175], v[188:191], v[40:43]
	v_mfma_f32_16x16x32_f16 v[28:31], v[164:167], v[196:199], v[28:31]
	v_mfma_f32_16x16x32_f16 v[24:27], v[172:175], v[196:199], v[24:27]
	v_mfma_f32_16x16x32_f16 v[12:15], v[164:167], v[204:207], v[12:15]
	v_mfma_f32_16x16x32_f16 v[8:11], v[172:175], v[204:207], v[8:11]
	s_barrier
	s_add_u32 s34, s82, 0x40080
	s_addc_u32 s35, s83, 0
	s_add_i32 s82, s84, s87
	s_mov_b32 m0, s82
	v_lshl_add_u64 v[148:149], s[34:35], 0, v[132:133]
	global_load_lds_dwordx4 v[148:149], off
	s_add_i32 m0, s82, 0x2000
	v_lshl_add_u64 v[148:149], s[34:35], 0, v[136:137]
	global_load_lds_dwordx4 v[148:149], off
	s_waitcnt vmcnt(6)
	s_barrier
	v_mfma_f32_16x16x32_f16 v[52:55], v[208:211], v[176:179], v[52:55]
	v_mfma_f32_16x16x32_f16 v[48:51], v[216:219], v[176:179], v[48:51]
	v_mfma_f32_16x16x32_f16 v[36:39], v[208:211], v[184:187], v[36:39]
	v_mfma_f32_16x16x32_f16 v[32:35], v[216:219], v[184:187], v[32:35]
	v_mfma_f32_16x16x32_f16 v[20:23], v[208:211], v[192:195], v[20:23]
	v_mfma_f32_16x16x32_f16 v[16:19], v[216:219], v[192:195], v[16:19]
	v_mfma_f32_16x16x32_f16 v[4:7], v[208:211], v[200:203], v[4:7]
	v_mfma_f32_16x16x32_f16 v[0:3], v[216:219], v[200:203], v[0:3]
	v_mfma_f32_16x16x32_f16 v[52:55], v[212:215], v[180:183], v[52:55]
	v_mfma_f32_16x16x32_f16 v[48:51], v[220:223], v[180:183], v[48:51]
	v_mfma_f32_16x16x32_f16 v[36:39], v[212:215], v[188:191], v[36:39]
	v_mfma_f32_16x16x32_f16 v[32:35], v[220:223], v[188:191], v[32:35]
	v_mfma_f32_16x16x32_f16 v[20:23], v[212:215], v[196:199], v[20:23]
	v_mfma_f32_16x16x32_f16 v[16:19], v[220:223], v[196:199], v[16:19]
	v_mfma_f32_16x16x32_f16 v[4:7], v[212:215], v[204:207], v[4:7]
	v_mfma_f32_16x16x32_f16 v[0:3], v[220:223], v[204:207], v[0:3]
	s_add_i32 s15, s15, 2
	s_add_u32 s80, s80, 0x100
	s_addc_u32 s81, s81, 0
	s_add_u32 vcc_hi, vcc_hi, 0x100
	s_addc_u32 s14, s14, 0
	s_cmp_gt_u32 s15, 13
	s_barrier
	s_cbranch_scc0 .LBB0_195
	v_lshl_add_u32 v148, s78, 8, v154
	s_cmp_gt_i32 s76, 15
	s_mov_b64 s[78:79], -1
	s_cbranch_scc0 .LBB0_218
	s_cmp_lt_u32 s76, 24
	s_cbranch_scc1 .LBB0_215
	v_and_b32_e32 v150, 64, v162
	v_xor_b32_e32 v149, 16, v162
	v_add_u32_e32 v150, 64, v150
	v_cmp_lt_i32_e32 vcc, v149, v150
	v_cvt_f16_f32_e32 v163, v124
	v_cvt_f16_f32_e32 v166, v126
	v_cndmask_b32_e32 v149, v162, v149, vcc
	v_lshlrev_b32_e32 v152, 2, v149
	v_xor_b32_e32 v149, 32, v162
	v_cmp_lt_i32_e32 vcc, v149, v150
	v_cvt_f16_f32_e32 v150, v125
	v_cvt_f32_f16_e32 v164, v163
	v_cvt_f16_f32_e32 v167, v127
	v_cvt_f32_f16_e32 v168, v166
	v_cvt_f32_f16_e32 v165, v150
	v_add_f32_e32 v164, 0, v164
	v_cvt_f16_f32_e32 v169, v122
	v_cvt_f16_f32_e32 v170, v123
	v_add_f32_e32 v164, v164, v165
	v_mul_f32_e32 v165, v165, v165
	v_fma_mix_f32 v163, v163, v163, v165 op_sel_hi:[1,1,0]
	v_cvt_f32_f16_e32 v165, v167
	v_add_f32_e32 v164, v164, v168
	v_cvt_f16_f32_e32 v168, v120
	v_fma_mix_f32 v163, v166, v166, v163 op_sel_hi:[1,1,0]
	v_add_f32_e32 v164, v164, v165
	v_cvt_f16_f32_e32 v165, v121
	v_cvt_f32_f16_e32 v166, v168
	v_fma_mix_f32 v163, v167, v167, v163 op_sel_hi:[1,1,0]
	v_cvt_f16_f32_e32 v171, v116
	v_cvt_f32_f16_e32 v167, v165
	v_fma_mix_f32 v163, v168, v168, v163 op_sel_hi:[1,1,0]
	v_add_f32_e32 v164, v164, v166
	v_cvt_f32_f16_e32 v166, v169
	v_fma_mix_f32 v163, v165, v165, v163 op_sel_hi:[1,1,0]
	v_add_f32_e32 v164, v164, v167
	v_fma_mix_f32 v163, v169, v169, v163 op_sel_hi:[1,1,0]
	v_cvt_f32_f16_e32 v169, v170
	v_add_f32_e32 v168, v164, v166
	v_cvt_f32_f16_e32 v172, v171
	v_fma_mix_f32 v163, v170, v170, v163 op_sel_hi:[1,1,0]
	v_add_f32_e32 v168, v168, v169
	v_cvt_f16_f32_e32 v169, v117
	v_add_f32_e32 v168, v168, v172
	v_cvt_f16_f32_e32 v172, v118
	v_fma_mix_f32 v163, v171, v171, v163 op_sel_hi:[1,1,0]
	v_cvt_f32_f16_e32 v170, v169
	v_fma_mix_f32 v163, v169, v169, v163 op_sel_hi:[1,1,0]
	v_cvt_f32_f16_e32 v171, v172
	v_cvt_f16_f32_e32 v169, v112
	v_add_f32_e32 v168, v168, v170
	v_cvt_f16_f32_e32 v170, v119
	v_add_f32_e32 v168, v168, v171
	v_fma_mix_f32 v163, v172, v172, v163 op_sel_hi:[1,1,0]
	v_cvt_f32_f16_e32 v171, v169
	v_cvt_f32_f16_e32 v173, v170
	v_cvt_f16_f32_e32 v172, v113
	v_fma_mix_f32 v163, v170, v170, v163 op_sel_hi:[1,1,0]
	v_cvt_f16_f32_e32 v170, v114
	v_add_f32_e32 v168, v168, v173
	v_add_f32_e32 v168, v168, v171
	v_cvt_f32_f16_e32 v171, v172
	v_cvt_f16_f32_e32 v173, v115
	v_fma_mix_f32 v163, v169, v169, v163 op_sel_hi:[1,1,0]
	v_cvt_f32_f16_e32 v169, v170
	v_add_f32_e32 v168, v168, v171
	v_cvt_f32_f16_e32 v171, v173
	v_fma_mix_f32 v163, v172, v172, v163 op_sel_hi:[1,1,0]
	v_add_f32_e32 v168, v168, v169
	v_fma_mix_f32 v163, v170, v170, v163 op_sel_hi:[1,1,0]
	v_add_f32_e32 v168, v168, v171
	v_fma_mix_f32 v163, v173, v173, v163 op_sel_hi:[1,1,0]
	ds_bpermute_b32 v172, v152, v168
	ds_bpermute_b32 v173, v152, v163
	v_cndmask_b32_e32 v149, v162, v149, vcc
	v_lshlrev_b32_e32 v153, 2, v149
	v_ashrrev_i32_e32 v149, 31, v148
	v_lshlrev_b64 v[150:151], 11, v[148:149]
	v_lshl_add_u32 v138, s76, 8, v156
	v_lshl_add_u64 v[150:151], s[18:19], 0, v[150:151]
	v_cvt_pk_f16_f32 v167, v122, v123
	v_cvt_pk_f16_f32 v166, v120, v121
	v_cvt_pk_f16_f32 v165, v126, v127
	v_cvt_pk_f16_f32 v164, v124, v125
	v_lshl_add_u64 v[170:171], v[138:139], 1, v[150:151]
	s_waitcnt lgkmcnt(0)
	v_add_f32_e32 v150, v168, v172
	v_add_f32_e32 v151, v163, v173
	global_store_dwordx4 v[170:171], v[164:167], off
	ds_bpermute_b32 v163, v153, v150
	ds_bpermute_b32 v164, v153, v151
	v_cvt_pk_f16_f32 v169, v114, v115
	v_cvt_pk_f16_f32 v168, v112, v113
	v_cvt_pk_f16_f32 v167, v118, v119
	v_cvt_pk_f16_f32 v166, v116, v117
	global_store_dwordx4 v[170:171], v[166:169], off offset:256
	s_and_saveexec_b64 s[78:79], s[0:1]
	s_cbranch_execz .LBB0_200
	v_lshl_add_u64 v[166:167], v[148:149], 3, s[20:21]
	s_waitcnt lgkmcnt(0)
	v_add_f32_e32 v149, v150, v163
	v_add_f32_e32 v150, v151, v164
	global_atomic_add_f32 v[166:167], v149, off
	global_atomic_add_f32 v[166:167], v150, off offset:4

; #define PG8_STAGE(bufoff, gbase, voff) do { _Pragma("unroll") for (int _i = 0; _i < 2; ++_i) \
;         __builtin_amdgcn_global_load_lds((const unsigned*)((const char*)(gbase) + (voff)[_i]), (LAS unsigned*)(lds + (bufoff) + ldsw + _i * 8192), 16, 0, 0); } while (0)
; #define PG8_LDA(dst, b, h) do { _Pragma("unroll") for (int m = 0; m < 4; ++m) _Pragma("unroll") for (int k = 0; k < 2; ++k) dst[m][k] = *(const LAS h16x8*)(lds + PG8_SA(b, h) + aoff + m * 2048 + k * 1024); } while (0)
; #define PG8_LDB(dst, b, h) do { _Pragma("unroll") for (int n = 0; n < 2; ++n) _Pragma("unroll") for (int k = 0; k < 2; ++k) dst[n][k] = *(const LAS h16x8*)(lds + PG8_SB(b, h) + boff + n * 2048 + k * 1024); } while (0)
; #define PG8_MMA(ai, bj, At, Bt) do { __builtin_amdgcn_s_setprio(1); _Pragma("unroll") for (int m = 0; m < 4; ++m) _Pragma("unroll") for (int n = 0; n < 2; ++n) _Pragma("unroll") for (int k = 0; k < 2; ++k) \
;         acc[ai][bj][m][n] = __builtin_amdgcn_mfma_f32_16x16x32_f16(Bt[n][k], At[m][k], acc[ai][bj][m][n], 0, 0, 0); __builtin_amdgcn_s_setprio(0); } while (0)
; #define PG8_WAIT_V(n) asm volatile("s_waitcnt vmcnt(" #n ")" ::: "memory")
; #define PG8_WAIT_L(n) asm volatile("s_waitcnt lgkmcnt(" #n ")" ::: "memory")
; #define PG8_BAR __builtin_amdgcn_s_barrier()
; #define PG8_SCHED __builtin_amdgcn_sched_barrier(0)
; template <class Epi>
; __device__ __forceinline__ void gemm_phase(LAS unsigned char* lds, const Gemm g, const StaticOrder& S, const Epi& E) {
;     ...
;             PG8_LDB(B0, 0, 0); PG8_SCHED; PG8_LDA(At, 0, 0); PG8_STAGE(PG8_SA(1, 1), a1 + hstep, voffA);
;             PG8_WAIT_L(8); PG8_BAR; PG8_WAIT_L(0); PG8_MMA(0, 0, At, B0); PG8_BAR; PG8_SCHED;
;             PG8_LDB(B1, 0, 1); PG8_STAGE(PG8_SB(0, 0), b2, voffB);
;             PG8_BAR; PG8_WAIT_L(0); PG8_MMA(0, 1, At, B1); PG8_BAR;
;             PG8_LDA(At, 0, 1); PG8_STAGE(PG8_SA(0, 0), a2, voffA);
;             PG8_BAR; PG8_WAIT_L(0); PG8_MMA(1, 0, At, B0); PG8_BAR; PG8_SCHED;
;             PG8_STAGE(PG8_SB(0, 1), b2 + hstep, voffB);
;             PG8_WAIT_V(6); PG8_BAR; PG8_MMA(1, 1, At, B1); PG8_BAR;
.LBB0_356:
	ds_read_b128 v[152:155], v149
	ds_read_b128 v[156:159], v149 offset:1024
	ds_read_b128 v[160:163], v149 offset:2048
	ds_read_b128 v[164:167], v149 offset:3072
	s_add_u32 s34, s46, 0xfff80080
	s_addc_u32 s35, s47, -1
	s_cmp_eq_u32 s15, 28
	s_cselect_b32 s53, s27, s35
	s_cselect_b32 s52, s94, s34
	s_cselect_b32 s49, s25, s14
	s_cselect_b32 s48, s95, s96
	v_lshl_add_u64 v[202:203], s[46:47], 0, v[138:139]
	s_add_i32 m0, s23, 0xc000
	ds_read_b128 v[170:173], v150
	ds_read_b128 v[174:177], v150 offset:1024
	ds_read_b128 v[178:181], v150 offset:2048
	ds_read_b128 v[182:185], v150 offset:3072
	ds_read_b128 v[186:189], v150 offset:4096
	ds_read_b128 v[190:193], v150 offset:5120
	ds_read_b128 v[194:197], v150 offset:6144
	ds_read_b128 v[198:201], v150 offset:7168
	global_load_lds_dwordx4 v[202:203], off
	s_add_i32 m0, s23, 0xe000
	v_lshl_add_u64 v[202:203], s[46:47], 0, v[140:141]
	global_load_lds_dwordx4 v[202:203], off
	s_waitcnt lgkmcnt(8)
	s_barrier
	s_waitcnt lgkmcnt(0)
	s_waitcnt lgkmcnt(0)
	v_mfma_f32_16x16x32_f16 v[124:127], v[152:155], v[170:173], v[124:127]
	v_mfma_f32_16x16x32_f16 v[120:123], v[160:163], v[170:173], v[120:123]
	v_mfma_f32_16x16x32_f16 v[116:119], v[152:155], v[178:181], v[116:119]
	v_mfma_f32_16x16x32_f16 v[112:115], v[160:163], v[178:181], v[112:115]
	v_mfma_f32_16x16x32_f16 v[100:103], v[152:155], v[186:189], v[100:103]
	v_mfma_f32_16x16x32_f16 v[96:99], v[160:163], v[186:189], v[96:99]
	v_mfma_f32_16x16x32_f16 v[84:87], v[152:155], v[194:197], v[84:87]
	v_mfma_f32_16x16x32_f16 v[80:83], v[160:163], v[194:197], v[80:83]
	v_mfma_f32_16x16x32_f16 v[124:127], v[156:159], v[174:177], v[124:127]
	v_mfma_f32_16x16x32_f16 v[120:123], v[164:167], v[174:177], v[120:123]
	v_mfma_f32_16x16x32_f16 v[116:119], v[156:159], v[182:185], v[116:119]
	v_mfma_f32_16x16x32_f16 v[112:115], v[164:167], v[182:185], v[112:115]
	v_mfma_f32_16x16x32_f16 v[100:103], v[156:159], v[190:193], v[100:103]
	v_mfma_f32_16x16x32_f16 v[96:99], v[164:167], v[190:193], v[96:99]
	v_mfma_f32_16x16x32_f16 v[84:87], v[156:159], v[198:201], v[84:87]
	v_mfma_f32_16x16x32_f16 v[80:83], v[164:167], v[198:201], v[80:83]
	s_barrier
	s_add_i32 s34, s88, s78
	v_lshl_add_u64 v[218:219], s[48:49], 0, v[132:133]
	s_mov_b32 m0, s34
	ds_read_b128 v[202:205], v151
	ds_read_b128 v[206:209], v151 offset:1024
	ds_read_b128 v[210:213], v151 offset:2048
	ds_read_b128 v[214:217], v151 offset:3072
	global_load_lds_dwordx4 v[218:219], off
	s_add_i32 m0, s34, 0x2000
	v_lshl_add_u64 v[220:221], s[48:49], 0, v[136:137]
	global_load_lds_dwordx4 v[220:221], off
	s_barrier
	s_waitcnt lgkmcnt(0)
	s_waitcnt lgkmcnt(0)
	v_mfma_f32_16x16x32_f16 v[108:111], v[202:205], v[170:173], v[108:111]
	v_mfma_f32_16x16x32_f16 v[104:107], v[210:213], v[170:173], v[104:107]
	v_mfma_f32_16x16x32_f16 v[92:95], v[202:205], v[178:181], v[92:95]
	v_mfma_f32_16x16x32_f16 v[88:91], v[210:213], v[178:181], v[88:91]
	v_mfma_f32_16x16x32_f16 v[76:79], v[202:205], v[186:189], v[76:79]
	v_mfma_f32_16x16x32_f16 v[72:75], v[210:213], v[186:189], v[72:75]
	v_mfma_f32_16x16x32_f16 v[68:71], v[202:205], v[194:197], v[68:71]
	v_mfma_f32_16x16x32_f16 v[64:67], v[210:213], v[194:197], v[64:67]
	v_mfma_f32_16x16x32_f16 v[108:111], v[206:209], v[174:177], v[108:111]
	v_mfma_f32_16x16x32_f16 v[104:107], v[214:217], v[174:177], v[104:107]
	v_mfma_f32_16x16x32_f16 v[92:95], v[206:209], v[182:185], v[92:95]
	v_mfma_f32_16x16x32_f16 v[88:91], v[214:217], v[182:185], v[88:91]
	v_mfma_f32_16x16x32_f16 v[76:79], v[206:209], v[190:193], v[76:79]
	v_mfma_f32_16x16x32_f16 v[72:75], v[214:217], v[190:193], v[72:75]
	v_mfma_f32_16x16x32_f16 v[68:71], v[206:209], v[198:201], v[68:71]
	v_mfma_f32_16x16x32_f16 v[64:67], v[214:217], v[198:201], v[64:67]
	s_mov_b32 m0, s23
	v_lshl_add_u64 v[222:223], s[52:53], 0, v[128:129]
	s_barrier
	ds_read_b128 v[170:173], v150 offset:16384
	ds_read_b128 v[174:177], v150 offset:17408
	ds_read_b128 v[178:181], v150 offset:18432
	ds_read_b128 v[182:185], v150 offset:19456
	ds_read_b128 v[186:189], v150 offset:20480
	ds_read_b128 v[190:193], v150 offset:21504
	ds_read_b128 v[194:197], v150 offset:22528
	ds_read_b128 v[198:201], v150 offset:23552
	global_load_lds_dwordx4 v[222:223], off
	s_mov_b32 m0, s80
	v_lshl_add_u64 v[224:225], s[52:53], 0, v[134:135]
	global_load_lds_dwordx4 v[224:225], off
	s_barrier
	s_waitcnt lgkmcnt(0)
	s_waitcnt lgkmcnt(0)
	v_mfma_f32_16x16x32_f16 v[60:63], v[152:155], v[170:173], v[60:63]
	v_mfma_f32_16x16x32_f16 v[56:59], v[160:163], v[170:173], v[56:59]
	v_mfma_f32_16x16x32_f16 v[52:55], v[152:155], v[178:181], v[52:55]
	v_mfma_f32_16x16x32_f16 v[48:51], v[160:163], v[178:181], v[48:51]
	v_mfma_f32_16x16x32_f16 v[36:39], v[152:155], v[186:189], v[36:39]
	v_mfma_f32_16x16x32_f16 v[32:35], v[160:163], v[186:189], v[32:35]
	v_mfma_f32_16x16x32_f16 v[20:23], v[152:155], v[194:197], v[20:23]
	v_mfma_f32_16x16x32_f16 v[16:19], v[160:163], v[194:197], v[16:19]
	v_mfma_f32_16x16x32_f16 v[60:63], v[156:159], v[174:177], v[60:63]
	v_mfma_f32_16x16x32_f16 v[56:59], v[164:167], v[174:177], v[56:59]
	v_mfma_f32_16x16x32_f16 v[52:55], v[156:159], v[182:185], v[52:55]
	v_mfma_f32_16x16x32_f16 v[48:51], v[164:167], v[182:185], v[48:51]
	v_mfma_f32_16x16x32_f16 v[36:39], v[156:159], v[190:193], v[36:39]
	v_mfma_f32_16x16x32_f16 v[32:35], v[164:167], v[190:193], v[32:35]
	v_mfma_f32_16x16x32_f16 v[20:23], v[156:159], v[198:201], v[20:23]
	v_mfma_f32_16x16x32_f16 v[16:19], v[164:167], v[198:201], v[16:19]
	s_barrier
; #define PG8_STAGE(bufoff, gbase, voff) do { _Pragma("unroll") for (int _i = 0; _i < 2; ++_i) \
;         __builtin_amdgcn_global_load_lds((const unsigned*)((const char*)(gbase) + (voff)[_i]), (LAS unsigned*)(lds + (bufoff) + ldsw + _i * 8192), 16, 0, 0); } while (0)
; #define PG8_LDA(dst, b, h) do { _Pragma("unroll") for (int m = 0; m < 4; ++m) _Pragma("unroll") for (int k = 0; k < 2; ++k) dst[m][k] = *(const LAS h16x8*)(lds + PG8_SA(b, h) + aoff + m * 2048 + k * 1024); } while (0)
; #define PG8_LDB(dst, b, h) do { _Pragma("unroll") for (int n = 0; n < 2; ++n) _Pragma("unroll") for (int k = 0; k < 2; ++k) dst[n][k] = *(const LAS h16x8*)(lds + PG8_SB(b, h) + boff + n * 2048 + k * 1024); } while (0)
; #define PG8_MMA(ai, bj, At, Bt) do { __builtin_amdgcn_s_setprio(1); _Pragma("unroll") for (int m = 0; m < 4; ++m) _Pragma("unroll") for (int n = 0; n < 2; ++n) _Pragma("unroll") for (int k = 0; k < 2; ++k) \
;         acc[ai][bj][m][n] = __builtin_amdgcn_mfma_f32_16x16x32_f16(Bt[n][k], At[m][k], acc[ai][bj][m][n], 0, 0, 0); __builtin_amdgcn_s_setprio(0); } while (0)
; #define PG8_WAIT_V(n) asm volatile("s_waitcnt vmcnt(" #n ")" ::: "memory")
; #define PG8_WAIT_L(n) asm volatile("s_waitcnt lgkmcnt(" #n ")" ::: "memory")
; #define PG8_BAR __builtin_amdgcn_s_barrier()
; #define PG8_SCHED __builtin_amdgcn_sched_barrier(0)
; template <class Epi>
; __device__ __forceinline__ void gemm_phase(LAS unsigned char* lds, const Gemm g, const StaticOrder& S, const Epi& E) {
;     ...
;             PG8_STAGE(PG8_SB(0, 1), b2 + hstep, voffB);
;             PG8_WAIT_V(6); PG8_BAR; PG8_MMA(1, 1, At, B1); PG8_BAR;
;             PG8_LDB(B0, 1, 0); PG8_SCHED; PG8_LDA(At, 1, 0); PG8_STAGE(PG8_SA(0, 1), a2 + hstep, voffA);
;             PG8_WAIT_L(8); PG8_BAR; PG8_WAIT_L(0); PG8_MMA(0, 0, At, B0); PG8_BAR; PG8_SCHED;
;             PG8_LDB(B1, 1, 1); PG8_STAGE(PG8_SB(1, 0), b3, voffB);
;             PG8_BAR; PG8_WAIT_L(0); PG8_MMA(0, 1, At, B1); PG8_BAR;
;             PG8_LDA(At, 1, 1); PG8_STAGE(PG8_SA(1, 0), a3, voffA);
;             PG8_BAR; PG8_WAIT_L(0); PG8_MMA(1, 0, At, B0); PG8_BAR; PG8_SCHED;
	s_add_u32 s34, s48, 0x80000
	s_addc_u32 s35, s49, 0
	s_add_i32 s97, s89, s78
	s_mov_b32 m0, s97
	v_lshl_add_u64 v[152:153], s[34:35], 0, v[132:133]
	global_load_lds_dwordx4 v[152:153], off
	s_add_i32 m0, s97, 0x2000
	v_lshl_add_u64 v[152:153], s[34:35], 0, v[136:137]
	global_load_lds_dwordx4 v[152:153], off
	s_waitcnt vmcnt(6)
	s_barrier
	v_mfma_f32_16x16x32_f16 v[44:47], v[202:205], v[170:173], v[44:47]
	v_mfma_f32_16x16x32_f16 v[40:43], v[210:213], v[170:173], v[40:43]
	v_mfma_f32_16x16x32_f16 v[28:31], v[202:205], v[178:181], v[28:31]
	v_mfma_f32_16x16x32_f16 v[24:27], v[210:213], v[178:181], v[24:27]
	v_mfma_f32_16x16x32_f16 v[12:15], v[202:205], v[186:189], v[12:15]
	v_mfma_f32_16x16x32_f16 v[8:11], v[210:213], v[186:189], v[8:11]
	v_mfma_f32_16x16x32_f16 v[4:7], v[202:205], v[194:197], v[4:7]
	v_mfma_f32_16x16x32_f16 v[0:3], v[210:213], v[194:197], v[0:3]
	v_mfma_f32_16x16x32_f16 v[44:47], v[206:209], v[174:177], v[44:47]
	v_mfma_f32_16x16x32_f16 v[40:43], v[214:217], v[174:177], v[40:43]
	v_mfma_f32_16x16x32_f16 v[28:31], v[206:209], v[182:185], v[28:31]
	v_mfma_f32_16x16x32_f16 v[24:27], v[214:217], v[182:185], v[24:27]
	v_mfma_f32_16x16x32_f16 v[12:15], v[206:209], v[190:193], v[12:15]
	v_mfma_f32_16x16x32_f16 v[8:11], v[214:217], v[190:193], v[8:11]
	v_mfma_f32_16x16x32_f16 v[4:7], v[206:209], v[198:201], v[4:7]
	v_mfma_f32_16x16x32_f16 v[0:3], v[214:217], v[198:201], v[0:3]
	s_add_i32 s97, 0, 0x18000
	v_add_u32_e32 v164, s97, v147
	s_barrier
	ds_read_b128 v[152:155], v164
	ds_read_b128 v[156:159], v164 offset:1024
	ds_read_b128 v[160:163], v164 offset:2048
	ds_read_b128 v[164:167], v164 offset:3072
	s_add_u32 s34, s52, 0x80000
	s_addc_u32 s35, s53, 0
	s_mov_b32 m0, s81
	v_lshl_add_u64 v[202:203], s[34:35], 0, v[128:129]
	ds_read_b128 v[170:173], v150 offset:32768
	ds_read_b128 v[174:177], v150 offset:33792
	ds_read_b128 v[178:181], v150 offset:34816
	ds_read_b128 v[182:185], v150 offset:35840
	ds_read_b128 v[186:189], v150 offset:36864
	ds_read_b128 v[190:193], v150 offset:37888
	ds_read_b128 v[194:197], v150 offset:38912
	ds_read_b128 v[198:201], v150 offset:39936
	global_load_lds_dwordx4 v[202:203], off
	s_mov_b32 m0, s82
	v_lshl_add_u64 v[202:203], s[34:35], 0, v[134:135]
	global_load_lds_dwordx4 v[202:203], off
	s_waitcnt lgkmcnt(8)
	s_barrier
	s_waitcnt lgkmcnt(0)
	s_waitcnt lgkmcnt(0)
	v_mfma_f32_16x16x32_f16 v[124:127], v[152:155], v[170:173], v[124:127]
	v_mfma_f32_16x16x32_f16 v[120:123], v[160:163], v[170:173], v[120:123]
	v_mfma_f32_16x16x32_f16 v[116:119], v[152:155], v[178:181], v[116:119]
	v_mfma_f32_16x16x32_f16 v[112:115], v[160:163], v[178:181], v[112:115]
	v_mfma_f32_16x16x32_f16 v[100:103], v[152:155], v[186:189], v[100:103]
	v_mfma_f32_16x16x32_f16 v[96:99], v[160:163], v[186:189], v[96:99]
	v_mfma_f32_16x16x32_f16 v[84:87], v[152:155], v[194:197], v[84:87]
	v_mfma_f32_16x16x32_f16 v[80:83], v[160:163], v[194:197], v[80:83]
	v_mfma_f32_16x16x32_f16 v[124:127], v[156:159], v[174:177], v[124:127]
	v_mfma_f32_16x16x32_f16 v[120:123], v[164:167], v[174:177], v[120:123]
	v_mfma_f32_16x16x32_f16 v[116:119], v[156:159], v[182:185], v[116:119]
	v_mfma_f32_16x16x32_f16 v[112:115], v[164:167], v[182:185], v[112:115]
	v_mfma_f32_16x16x32_f16 v[100:103], v[156:159], v[190:193], v[100:103]
	v_mfma_f32_16x16x32_f16 v[96:99], v[164:167], v[190:193], v[96:99]
	v_mfma_f32_16x16x32_f16 v[84:87], v[156:159], v[198:201], v[84:87]
	v_mfma_f32_16x16x32_f16 v[80:83], v[164:167], v[198:201], v[80:83]
	s_barrier
	s_add_i32 s52, 0, 0x1c000
	s_add_i32 s34, s97, s78
	v_add_u32_e32 v169, s52, v147
	v_lshl_add_u64 v[218:219], v[218:219], 0, s[8:9]
	s_mov_b32 m0, s34
	ds_read_b128 v[202:205], v169
	ds_read_b128 v[206:209], v169 offset:1024
	ds_read_b128 v[210:213], v169 offset:2048
	ds_read_b128 v[214:217], v169 offset:3072
	global_load_lds_dwordx4 v[218:219], off
	s_add_i32 m0, s34, 0x2000
	v_lshl_add_u64 v[218:219], v[220:221], 0, s[8:9]
	global_load_lds_dwordx4 v[218:219], off
	s_barrier
	s_waitcnt lgkmcnt(0)
	s_waitcnt lgkmcnt(0)
	v_mfma_f32_16x16x32_f16 v[108:111], v[202:205], v[170:173], v[108:111]
	v_mfma_f32_16x16x32_f16 v[104:107], v[210:213], v[170:173], v[104:107]
	v_mfma_f32_16x16x32_f16 v[92:95], v[202:205], v[178:181], v[92:95]
	v_mfma_f32_16x16x32_f16 v[88:91], v[210:213], v[178:181], v[88:91]
	v_mfma_f32_16x16x32_f16 v[76:79], v[202:205], v[186:189], v[76:79]
	v_mfma_f32_16x16x32_f16 v[72:75], v[210:213], v[186:189], v[72:75]
	v_mfma_f32_16x16x32_f16 v[68:71], v[202:205], v[194:197], v[68:71]
	v_mfma_f32_16x16x32_f16 v[64:67], v[210:213], v[194:197], v[64:67]
	v_mfma_f32_16x16x32_f16 v[108:111], v[206:209], v[174:177], v[108:111]
	v_mfma_f32_16x16x32_f16 v[104:107], v[214:217], v[174:177], v[104:107]
	v_mfma_f32_16x16x32_f16 v[92:95], v[206:209], v[182:185], v[92:95]
	v_mfma_f32_16x16x32_f16 v[88:91], v[214:217], v[182:185], v[88:91]
	v_mfma_f32_16x16x32_f16 v[76:79], v[206:209], v[190:193], v[76:79]
	v_mfma_f32_16x16x32_f16 v[72:75], v[214:217], v[190:193], v[72:75]
	v_mfma_f32_16x16x32_f16 v[68:71], v[206:209], v[198:201], v[68:71]
	v_mfma_f32_16x16x32_f16 v[64:67], v[214:217], v[198:201], v[64:67]
	s_mov_b32 m0, s85
	v_lshl_add_u64 v[218:219], v[222:223], 0, s[8:9]
	s_barrier
	ds_read_b128 v[170:173], v150 offset:49152
	ds_read_b128 v[174:177], v150 offset:50176
	ds_read_b128 v[178:181], v150 offset:51200
	ds_read_b128 v[182:185], v150 offset:52224
	ds_read_b128 v[186:189], v150 offset:53248
	ds_read_b128 v[190:193], v150 offset:54272
	ds_read_b128 v[194:197], v150 offset:55296
	ds_read_b128 v[198:201], v150 offset:56320
	global_load_lds_dwordx4 v[218:219], off
	s_mov_b32 m0, s86
	v_lshl_add_u64 v[218:219], v[224:225], 0, s[8:9]
	global_load_lds_dwordx4 v[218:219], off
	s_barrier
; #define PG8_STAGE(bufoff, gbase, voff) do { _Pragma("unroll") for (int _i = 0; _i < 2; ++_i) \
;         __builtin_amdgcn_global_load_lds((const unsigned*)((const char*)(gbase) + (voff)[_i]), (LAS unsigned*)(lds + (bufoff) + ldsw + _i * 8192), 16, 0, 0); } while (0)
; #define PG8_MMA(ai, bj, At, Bt) do { __builtin_amdgcn_s_setprio(1); _Pragma("unroll") for (int m = 0; m < 4; ++m) _Pragma("unroll") for (int n = 0; n < 2; ++n) _Pragma("unroll") for (int k = 0; k < 2; ++k) \
;         acc[ai][bj][m][n] = __builtin_amdgcn_mfma_f32_16x16x32_f16(Bt[n][k], At[m][k], acc[ai][bj][m][n], 0, 0, 0); __builtin_amdgcn_s_setprio(0); } while (0)
; #define PG8_WAIT_V(n) asm volatile("s_waitcnt vmcnt(" #n ")" ::: "memory")
; #define PG8_WAIT_L(n) asm volatile("s_waitcnt lgkmcnt(" #n ")" ::: "memory")
; #define PG8_BAR __builtin_amdgcn_s_barrier()
; #define PG8_SCHED __builtin_amdgcn_sched_barrier(0)
; template <class Epi>
; __device__ __forceinline__ void gemm_phase(LAS unsigned char* lds, const Gemm g, const StaticOrder& S, const Epi& E) {
;     ...
;             PG8_BAR; PG8_WAIT_L(0); PG8_MMA(1, 0, At, B0); PG8_BAR; PG8_SCHED;
;             PG8_STAGE(PG8_SB(1, 1), b3 + hstep, voffB);
;             PG8_WAIT_V(6); PG8_BAR; PG8_MMA(1, 1, At, B1); PG8_BAR;
	s_waitcnt lgkmcnt(0)
	s_waitcnt lgkmcnt(0)
	v_mfma_f32_16x16x32_f16 v[60:63], v[152:155], v[170:173], v[60:63]
	v_mfma_f32_16x16x32_f16 v[56:59], v[160:163], v[170:173], v[56:59]
	v_mfma_f32_16x16x32_f16 v[52:55], v[152:155], v[178:181], v[52:55]
	v_mfma_f32_16x16x32_f16 v[48:51], v[160:163], v[178:181], v[48:51]
	v_mfma_f32_16x16x32_f16 v[36:39], v[152:155], v[186:189], v[36:39]
	v_mfma_f32_16x16x32_f16 v[32:35], v[160:163], v[186:189], v[32:35]
	v_mfma_f32_16x16x32_f16 v[20:23], v[152:155], v[194:197], v[20:23]
	v_mfma_f32_16x16x32_f16 v[16:19], v[160:163], v[194:197], v[16:19]
	v_mfma_f32_16x16x32_f16 v[60:63], v[156:159], v[174:177], v[60:63]
	v_mfma_f32_16x16x32_f16 v[56:59], v[164:167], v[174:177], v[56:59]
	v_mfma_f32_16x16x32_f16 v[52:55], v[156:159], v[182:185], v[52:55]
	v_mfma_f32_16x16x32_f16 v[48:51], v[164:167], v[182:185], v[48:51]
	v_mfma_f32_16x16x32_f16 v[36:39], v[156:159], v[190:193], v[36:39]
	v_mfma_f32_16x16x32_f16 v[32:35], v[164:167], v[190:193], v[32:35]
	v_mfma_f32_16x16x32_f16 v[20:23], v[156:159], v[198:201], v[20:23]
	v_mfma_f32_16x16x32_f16 v[16:19], v[164:167], v[198:201], v[16:19]
	s_barrier
	s_add_u32 s34, s48, 0x80080
	s_addc_u32 s35, s49, 0
	s_add_i32 s48, s52, s78
	s_mov_b32 m0, s48
	v_lshl_add_u64 v[152:153], s[34:35], 0, v[132:133]
	global_load_lds_dwordx4 v[152:153], off
	s_add_i32 m0, s48, 0x2000
	v_lshl_add_u64 v[152:153], s[34:35], 0, v[136:137]
	global_load_lds_dwordx4 v[152:153], off
	s_waitcnt vmcnt(6)
	s_barrier
	v_mfma_f32_16x16x32_f16 v[44:47], v[202:205], v[170:173], v[44:47]
	v_mfma_f32_16x16x32_f16 v[40:43], v[210:213], v[170:173], v[40:43]
	v_mfma_f32_16x16x32_f16 v[28:31], v[202:205], v[178:181], v[28:31]
	v_mfma_f32_16x16x32_f16 v[24:27], v[210:213], v[178:181], v[24:27]
	v_mfma_f32_16x16x32_f16 v[12:15], v[202:205], v[186:189], v[12:15]
	v_mfma_f32_16x16x32_f16 v[8:11], v[210:213], v[186:189], v[8:11]
	v_mfma_f32_16x16x32_f16 v[4:7], v[202:205], v[194:197], v[4:7]
	v_mfma_f32_16x16x32_f16 v[0:3], v[210:213], v[194:197], v[0:3]
	v_mfma_f32_16x16x32_f16 v[44:47], v[206:209], v[174:177], v[44:47]
	v_mfma_f32_16x16x32_f16 v[40:43], v[214:217], v[174:177], v[40:43]
	v_mfma_f32_16x16x32_f16 v[28:31], v[206:209], v[182:185], v[28:31]
	v_mfma_f32_16x16x32_f16 v[24:27], v[214:217], v[182:185], v[24:27]
	v_mfma_f32_16x16x32_f16 v[12:15], v[206:209], v[190:193], v[12:15]
	v_mfma_f32_16x16x32_f16 v[8:11], v[214:217], v[190:193], v[8:11]
	v_mfma_f32_16x16x32_f16 v[4:7], v[206:209], v[198:201], v[4:7]
	v_mfma_f32_16x16x32_f16 v[0:3], v[214:217], v[198:201], v[0:3]
	s_add_i32 s15, s15, 2
	s_add_u32 s46, s46, 0x100
	s_addc_u32 s47, s47, 0
	s_add_u32 s96, s96, 0x100
	s_addc_u32 s14, s14, 0
	s_cmp_gt_u32 s15, 29
	s_barrier
	s_cbranch_scc0 .LBB0_356
; #define PG8_WAIT_V(n) asm volatile("s_waitcnt vmcnt(" #n ")" ::: "memory")
; #define PG8_BAR __builtin_amdgcn_s_barrier()
; template <class Epi>
; __device__ __forceinline__ void gemm_phase(LAS unsigned char* lds, const Gemm g, const StaticOrder& S, const Epi& E) {
;     ...
;         cur = nxt; cA = nA; cB = nB; ++ui;
;     }
;     PG8_WAIT_V(0);
;     if (wr == 0) PG8_BAR;
;     __device__ __forceinline__ void operator()(const f32x4 (&acc)[2][2][4][2], const pg8::Unit& u, int wr, int wc, int fr, int fq) const {
;         const int row0 = u.pm * 256 + wr * 64 + fr, col0 = u.pn * 256 + wc * 32 + 8 * fq;
; #pragma unroll
;         for (int ai = 0; ai < 2; ++ai)
; #pragma unroll
;             for (int m = 0; m < 4; ++m) { const size_t r = (size_t)(row0 + ai * 128 + m * 16);
; #pragma unroll
;                 for (int bj = 0; bj < 2; ++bj) { const f32x4 v0 = acc[ai][bj][m][0], v1 = acc[ai][bj][m][1]; h16x8 o;
; #pragma unroll
;                     for (int e = 0; e < 4; ++e) { o[e] = (h16)v0[e]; o[4 + e] = (h16)v1[e]; }
;                     *(h16x8*)(O1 + r * 1024 + col0 + bj * 128) = o; } }
	v_lshl_add_u32 v152, s22, 8, v146
	v_lshl_or_b32 v154, s93, 8, v148
	v_ashrrev_i32_e32 v153, 31, v152
	v_ashrrev_i32_e32 v155, 31, v154
	v_lshlrev_b64 v[156:157], 11, v[152:153]
	v_cvt_pk_f16_f32 v123, v122, v123
	v_cvt_pk_f16_f32 v122, v120, v121
	v_cvt_pk_f16_f32 v121, v126, v127
	v_cvt_pk_f16_f32 v120, v124, v125
	v_lshl_add_u64 v[124:125], s[6:7], 0, v[156:157]
	v_lshlrev_b64 v[126:127], 1, v[154:155]
	v_lshl_add_u64 v[124:125], v[124:125], 0, v[126:127]
	v_cvt_pk_f16_f32 v107, v106, v107
	v_cvt_pk_f16_f32 v106, v104, v105
	v_cvt_pk_f16_f32 v105, v110, v111
	v_cvt_pk_f16_f32 v104, v108, v109
	global_store_dwordx4 v[124:125], v[104:107], off offset:256
	v_cvt_pk_f16_f32 v91, v90, v91
	v_cvt_pk_f16_f32 v90, v88, v89
	v_or_b32_e32 v104, 16, v152
	v_ashrrev_i32_e32 v105, 31, v104
	v_lshlrev_b64 v[108:109], 11, v[104:105]
	v_lshl_add_u64 v[108:109], s[6:7], 0, v[108:109]
	v_lshl_add_u64 v[108:109], v[108:109], 0, v[126:127]
	v_cvt_pk_f16_f32 v89, v94, v95
	v_cvt_pk_f16_f32 v88, v92, v93
	global_store_dwordx4 v[108:109], v[88:91], off offset:256
	v_cvt_pk_f16_f32 v59, v58, v59
	v_cvt_pk_f16_f32 v58, v56, v57
	v_or_b32_e32 v88, 32, v152
	v_ashrrev_i32_e32 v89, 31, v88
	v_cvt_pk_f16_f32 v57, v62, v63
	v_add_co_u32_e32 v62, vcc, s90, v124
	v_lshlrev_b64 v[92:93], 11, v[88:89]
	s_nop 0
	v_addc_co_u32_e32 v63, vcc, 0, v125, vcc
	v_lshl_add_u64 v[92:93], s[6:7], 0, v[92:93]
	v_cvt_pk_f16_f32 v43, v42, v43
	v_cvt_pk_f16_f32 v42, v40, v41
	v_cvt_pk_f16_f32 v41, v46, v47
	v_add_co_u32_e32 v46, vcc, s91, v124
	v_lshl_add_u64 v[92:93], v[92:93], 0, v[126:127]
	v_cvt_pk_f16_f32 v75, v74, v75
	v_cvt_pk_f16_f32 v74, v72, v73
	v_cvt_pk_f16_f32 v73, v78, v79
	v_cvt_pk_f16_f32 v72, v76, v77
	v_addc_co_u32_e32 v47, vcc, 0, v125, vcc
	global_store_dwordx4 v[92:93], v[72:75], off offset:256
	v_cvt_pk_f16_f32 v27, v26, v27
	v_cvt_pk_f16_f32 v26, v24, v25
	v_or_b32_e32 v72, 48, v152
	v_cvt_pk_f16_f32 v25, v30, v31
	v_add_co_u32_e32 v30, vcc, s92, v124
	v_ashrrev_i32_e32 v73, 31, v72
	s_nop 0
	v_addc_co_u32_e32 v31, vcc, 0, v125, vcc
	v_lshlrev_b64 v[76:77], 11, v[72:73]
	v_cvt_pk_f16_f32 v11, v10, v11
	v_cvt_pk_f16_f32 v10, v8, v9
	v_cvt_pk_f16_f32 v9, v14, v15
	v_add_co_u32_e32 v14, vcc, 0x58000, v124
	v_lshl_add_u64 v[76:77], s[6:7], 0, v[76:77]
	v_cvt_pk_f16_f32 v56, v60, v61
	v_lshl_add_u64 v[60:61], v[124:125], 0, s[10:11]
	v_cvt_pk_f16_f32 v40, v44, v45
	v_lshl_add_u64 v[44:45], v[124:125], 0, s[12:13]
	v_cvt_pk_f16_f32 v24, v28, v29
	v_lshl_add_u64 v[28:29], v[124:125], 0, s[18:19]
	v_cvt_pk_f16_f32 v8, v12, v13
	v_addc_co_u32_e32 v15, vcc, 0, v125, vcc
	v_cvt_pk_f16_f32 v107, v114, v115
	v_cvt_pk_f16_f32 v106, v112, v113
	v_cvt_pk_f16_f32 v105, v118, v119
	v_cvt_pk_f16_f32 v104, v116, v117
	v_cvt_pk_f16_f32 v91, v98, v99
	v_cvt_pk_f16_f32 v90, v96, v97
	v_cvt_pk_f16_f32 v89, v102, v103
	v_cvt_pk_f16_f32 v88, v100, v101
	v_cvt_pk_f16_f32 v75, v82, v83
	v_cvt_pk_f16_f32 v74, v80, v81
	v_cvt_pk_f16_f32 v73, v86, v87
	v_cvt_pk_f16_f32 v72, v84, v85
	v_lshl_add_u64 v[76:77], v[76:77], 0, v[126:127]
	v_cvt_pk_f16_f32 v67, v66, v67
	v_cvt_pk_f16_f32 v66, v64, v65
	v_cvt_pk_f16_f32 v65, v70, v71
	v_cvt_pk_f16_f32 v64, v68, v69
	global_store_dwordx4 v[60:61], v[40:43], off offset:256
	global_store_dwordx4 v[44:45], v[24:27], off offset:256
	global_store_dwordx4 v[28:29], v[8:11], off offset:256
	v_cvt_pk_f16_f32 v43, v50, v51
	v_cvt_pk_f16_f32 v42, v48, v49
	v_cvt_pk_f16_f32 v41, v54, v55
	v_cvt_pk_f16_f32 v40, v52, v53
	v_cvt_pk_f16_f32 v27, v34, v35
	v_cvt_pk_f16_f32 v26, v32, v33
	v_cvt_pk_f16_f32 v25, v38, v39
	v_cvt_pk_f16_f32 v24, v36, v37
	v_cvt_pk_f16_f32 v11, v18, v19
	v_cvt_pk_f16_f32 v10, v16, v17
	v_cvt_pk_f16_f32 v9, v22, v23
	v_cvt_pk_f16_f32 v8, v20, v21
	v_lshl_add_u64 v[12:13], v[124:125], 0, s[20:21]
	v_cvt_pk_f16_f32 v3, v2, v3
	v_cvt_pk_f16_f32 v2, v0, v1
	v_cvt_pk_f16_f32 v1, v6, v7
	v_cvt_pk_f16_f32 v0, v4, v5
	s_and_b64 vcc, exec, s[0:1]
	s_mov_b32 s93, s24
	s_mov_b32 s22, s26
	s_mov_b64 s[48:49], s[30:31]
	s_mov_b64 s[46:47], s[28:29]
	global_store_dwordx4 v[124:125], v[120:123], off
	global_store_dwordx4 v[108:109], v[104:107], off
	global_store_dwordx4 v[92:93], v[88:91], off
	global_store_dwordx4 v[76:77], v[72:75], off
	global_store_dwordx4 v[76:77], v[64:67], off offset:256
	global_store_dwordx4 v[62:63], v[56:59], off
	global_store_dwordx4 v[46:47], v[40:43], off
	global_store_dwordx4 v[30:31], v[24:27], off
	global_store_dwordx4 v[14:15], v[8:11], off
	global_store_dwordx4 v[12:13], v[0:3], off offset:256
	s_cbranch_vccz .LBB0_349
	s_waitcnt vmcnt(0)
	s_cmpk_gt_u32 s33, 0xff
	s_cbranch_scc1 .LBB0_360
	s_barrier

; #define PG8_STAGE(bufoff, gbase, voff) do { _Pragma("unroll") for (int _i = 0; _i < 2; ++_i) \
;         __builtin_amdgcn_global_load_lds((const unsigned*)((const char*)(gbase) + (voff)[_i]), (LAS unsigned*)(lds + (bufoff) + ldsw + _i * 8192), 16, 0, 0); } while (0)
; #define PG8_LDA(dst, b, h) do { _Pragma("unroll") for (int m = 0; m < 4; ++m) _Pragma("unroll") for (int k = 0; k < 2; ++k) dst[m][k] = *(const LAS h16x8*)(lds + PG8_SA(b, h) + aoff + m * 2048 + k * 1024); } while (0)
; #define PG8_LDB(dst, b, h) do { _Pragma("unroll") for (int n = 0; n < 2; ++n) _Pragma("unroll") for (int k = 0; k < 2; ++k) dst[n][k] = *(const LAS h16x8*)(lds + PG8_SB(b, h) + boff + n * 2048 + k * 1024); } while (0)
; #define PG8_MMA(ai, bj, At, Bt) do { __builtin_amdgcn_s_setprio(1); _Pragma("unroll") for (int m = 0; m < 4; ++m) _Pragma("unroll") for (int n = 0; n < 2; ++n) _Pragma("unroll") for (int k = 0; k < 2; ++k) \
;         acc[ai][bj][m][n] = __builtin_amdgcn_mfma_f32_16x16x32_f16(Bt[n][k], At[m][k], acc[ai][bj][m][n], 0, 0, 0); __builtin_amdgcn_s_setprio(0); } while (0)
; #define PG8_WAIT_V(n) asm volatile("s_waitcnt vmcnt(" #n ")" ::: "memory")
; #define PG8_WAIT_L(n) asm volatile("s_waitcnt lgkmcnt(" #n ")" ::: "memory")
; #define PG8_BAR __builtin_amdgcn_s_barrier()
; #define PG8_SCHED __builtin_amdgcn_sched_barrier(0)
; template <class Epi>
; __device__ __forceinline__ void gemm_phase(LAS unsigned char* lds, const Gemm g, const StaticOrder& S, const Epi& E) {
;     ...
;             PG8_LDB(B0, 0, 0); PG8_SCHED; PG8_LDA(At, 0, 0); PG8_STAGE(PG8_SA(1, 1), a1 + hstep, voffA);
;             PG8_WAIT_L(8); PG8_BAR; PG8_WAIT_L(0); PG8_MMA(0, 0, At, B0); PG8_BAR; PG8_SCHED;
;             PG8_LDB(B1, 0, 1); PG8_STAGE(PG8_SB(0, 0), b2, voffB);
;             PG8_BAR; PG8_WAIT_L(0); PG8_MMA(0, 1, At, B1); PG8_BAR;
;             PG8_LDA(At, 0, 1); PG8_STAGE(PG8_SA(0, 0), a2, voffA);
;             PG8_BAR; PG8_WAIT_L(0); PG8_MMA(1, 0, At, B0); PG8_BAR; PG8_SCHED;
;             PG8_STAGE(PG8_SB(0, 1), b2 + hstep, voffB);
;             PG8_WAIT_V(6); PG8_BAR; PG8_MMA(1, 1, At, B1); PG8_BAR;
.LBB0_485:
	ds_read_b128 v[148:151], v165
	ds_read_b128 v[152:155], v165 offset:1024
	ds_read_b128 v[156:159], v165 offset:2048
	ds_read_b128 v[170:173], v165 offset:3072
	s_add_u32 s34, s76, 0xfffc0080
	s_addc_u32 s35, s77, -1
	s_cmp_eq_u32 s15, 12
	s_cselect_b32 s81, s47, s35
	s_cselect_b32 s80, s55, s34
	s_cselect_b32 s79, s31, s14
	s_cselect_b32 s78, s57, vcc_lo
	v_lshl_add_u64 v[160:161], s[76:77], 0, v[140:141]
	s_add_i32 m0, s85, 0xc000
	ds_read_b128 v[174:177], v166
	ds_read_b128 v[178:181], v166 offset:1024
	ds_read_b128 v[182:185], v166 offset:2048
	ds_read_b128 v[186:189], v166 offset:3072
	ds_read_b128 v[190:193], v166 offset:4096
	ds_read_b128 v[194:197], v166 offset:5120
	ds_read_b128 v[198:201], v166 offset:6144
	ds_read_b128 v[202:205], v166 offset:7168
	global_load_lds_dwordx4 v[160:161], off
	s_add_i32 m0, s85, 0xe000
	v_lshl_add_u64 v[160:161], s[76:77], 0, v[142:143]
	global_load_lds_dwordx4 v[160:161], off
	s_waitcnt lgkmcnt(8)
	s_barrier
	s_waitcnt lgkmcnt(0)
	s_waitcnt lgkmcnt(0)
	v_mfma_f32_16x16x32_f16 v[124:127], v[148:151], v[174:177], v[124:127]
	v_mfma_f32_16x16x32_f16 v[120:123], v[156:159], v[174:177], v[120:123]
	v_mfma_f32_16x16x32_f16 v[116:119], v[148:151], v[182:185], v[116:119]
	v_mfma_f32_16x16x32_f16 v[112:115], v[156:159], v[182:185], v[112:115]
	v_mfma_f32_16x16x32_f16 v[108:111], v[148:151], v[190:193], v[108:111]
	v_mfma_f32_16x16x32_f16 v[104:107], v[156:159], v[190:193], v[104:107]
	v_mfma_f32_16x16x32_f16 v[100:103], v[148:151], v[198:201], v[100:103]
	v_mfma_f32_16x16x32_f16 v[96:99], v[156:159], v[198:201], v[96:99]
	v_mfma_f32_16x16x32_f16 v[124:127], v[152:155], v[178:181], v[124:127]
	v_mfma_f32_16x16x32_f16 v[120:123], v[170:173], v[178:181], v[120:123]
	v_mfma_f32_16x16x32_f16 v[116:119], v[152:155], v[186:189], v[116:119]
	v_mfma_f32_16x16x32_f16 v[112:115], v[170:173], v[186:189], v[112:115]
	v_mfma_f32_16x16x32_f16 v[108:111], v[152:155], v[194:197], v[108:111]
	v_mfma_f32_16x16x32_f16 v[104:107], v[170:173], v[194:197], v[104:107]
	v_mfma_f32_16x16x32_f16 v[100:103], v[152:155], v[202:205], v[100:103]
	v_mfma_f32_16x16x32_f16 v[96:99], v[170:173], v[202:205], v[96:99]
	s_barrier
	s_add_i32 s34, s95, s84
	v_lshl_add_u64 v[160:161], s[78:79], 0, v[132:133]
	s_mov_b32 m0, s34
	ds_read_b128 v[206:209], v167
	ds_read_b128 v[210:213], v167 offset:1024
	ds_read_b128 v[214:217], v167 offset:2048
	ds_read_b128 v[218:221], v167 offset:3072
	global_load_lds_dwordx4 v[160:161], off
	s_add_i32 m0, s34, 0x2000
	v_lshl_add_u64 v[222:223], s[78:79], 0, v[136:137]
	global_load_lds_dwordx4 v[222:223], off
	s_barrier
	s_waitcnt lgkmcnt(0)
	s_waitcnt lgkmcnt(0)
	v_mfma_f32_16x16x32_f16 v[60:63], v[206:209], v[174:177], v[60:63]
	v_mfma_f32_16x16x32_f16 v[56:59], v[214:217], v[174:177], v[56:59]
	v_mfma_f32_16x16x32_f16 v[52:55], v[206:209], v[182:185], v[52:55]
	v_mfma_f32_16x16x32_f16 v[48:51], v[214:217], v[182:185], v[48:51]
	v_mfma_f32_16x16x32_f16 v[44:47], v[206:209], v[190:193], v[44:47]
	v_mfma_f32_16x16x32_f16 v[40:43], v[214:217], v[190:193], v[40:43]
	v_mfma_f32_16x16x32_f16 v[36:39], v[206:209], v[198:201], v[36:39]
	v_mfma_f32_16x16x32_f16 v[32:35], v[214:217], v[198:201], v[32:35]
	v_mfma_f32_16x16x32_f16 v[60:63], v[210:213], v[178:181], v[60:63]
	v_mfma_f32_16x16x32_f16 v[56:59], v[218:221], v[178:181], v[56:59]
	v_mfma_f32_16x16x32_f16 v[52:55], v[210:213], v[186:189], v[52:55]
	v_mfma_f32_16x16x32_f16 v[48:51], v[218:221], v[186:189], v[48:51]
	v_mfma_f32_16x16x32_f16 v[44:47], v[210:213], v[194:197], v[44:47]
	v_mfma_f32_16x16x32_f16 v[40:43], v[218:221], v[194:197], v[40:43]
	v_mfma_f32_16x16x32_f16 v[36:39], v[210:213], v[202:205], v[36:39]
	v_mfma_f32_16x16x32_f16 v[32:35], v[218:221], v[202:205], v[32:35]
	s_mov_b32 m0, s85
	v_lshl_add_u64 v[224:225], s[80:81], 0, v[128:129]
	s_barrier
	ds_read_b128 v[174:177], v166 offset:16384
	ds_read_b128 v[178:181], v166 offset:17408
	ds_read_b128 v[182:185], v166 offset:18432
	ds_read_b128 v[186:189], v166 offset:19456
	ds_read_b128 v[190:193], v166 offset:20480
	ds_read_b128 v[194:197], v166 offset:21504
	ds_read_b128 v[198:201], v166 offset:22528
	ds_read_b128 v[202:205], v166 offset:23552
	global_load_lds_dwordx4 v[224:225], off
	s_mov_b32 m0, s86
	v_lshl_add_u64 v[226:227], s[80:81], 0, v[134:135]
	global_load_lds_dwordx4 v[226:227], off
	s_barrier
	s_waitcnt lgkmcnt(0)
	s_waitcnt lgkmcnt(0)
	v_mfma_f32_16x16x32_f16 v[92:95], v[148:151], v[174:177], v[92:95]
	v_mfma_f32_16x16x32_f16 v[88:91], v[156:159], v[174:177], v[88:91]
	v_mfma_f32_16x16x32_f16 v[84:87], v[148:151], v[182:185], v[84:87]
	v_mfma_f32_16x16x32_f16 v[80:83], v[156:159], v[182:185], v[80:83]
	v_mfma_f32_16x16x32_f16 v[76:79], v[148:151], v[190:193], v[76:79]
	v_mfma_f32_16x16x32_f16 v[72:75], v[156:159], v[190:193], v[72:75]
	v_mfma_f32_16x16x32_f16 v[68:71], v[148:151], v[198:201], v[68:71]
	v_mfma_f32_16x16x32_f16 v[64:67], v[156:159], v[198:201], v[64:67]
	v_mfma_f32_16x16x32_f16 v[92:95], v[152:155], v[178:181], v[92:95]
	v_mfma_f32_16x16x32_f16 v[88:91], v[170:173], v[178:181], v[88:91]
	v_mfma_f32_16x16x32_f16 v[84:87], v[152:155], v[186:189], v[84:87]
	v_mfma_f32_16x16x32_f16 v[80:83], v[170:173], v[186:189], v[80:83]
	v_mfma_f32_16x16x32_f16 v[76:79], v[152:155], v[194:197], v[76:79]
	v_mfma_f32_16x16x32_f16 v[72:75], v[170:173], v[194:197], v[72:75]
	v_mfma_f32_16x16x32_f16 v[68:71], v[152:155], v[202:205], v[68:71]
	v_mfma_f32_16x16x32_f16 v[64:67], v[170:173], v[202:205], v[64:67]
	s_barrier
; #define PG8_STAGE(bufoff, gbase, voff) do { _Pragma("unroll") for (int _i = 0; _i < 2; ++_i) \
;         __builtin_amdgcn_global_load_lds((const unsigned*)((const char*)(gbase) + (voff)[_i]), (LAS unsigned*)(lds + (bufoff) + ldsw + _i * 8192), 16, 0, 0); } while (0)
; #define PG8_LDA(dst, b, h) do { _Pragma("unroll") for (int m = 0; m < 4; ++m) _Pragma("unroll") for (int k = 0; k < 2; ++k) dst[m][k] = *(const LAS h16x8*)(lds + PG8_SA(b, h) + aoff + m * 2048 + k * 1024); } while (0)
; #define PG8_LDB(dst, b, h) do { _Pragma("unroll") for (int n = 0; n < 2; ++n) _Pragma("unroll") for (int k = 0; k < 2; ++k) dst[n][k] = *(const LAS h16x8*)(lds + PG8_SB(b, h) + boff + n * 2048 + k * 1024); } while (0)
; #define PG8_MMA(ai, bj, At, Bt) do { __builtin_amdgcn_s_setprio(1); _Pragma("unroll") for (int m = 0; m < 4; ++m) _Pragma("unroll") for (int n = 0; n < 2; ++n) _Pragma("unroll") for (int k = 0; k < 2; ++k) \
;         acc[ai][bj][m][n] = __builtin_amdgcn_mfma_f32_16x16x32_f16(Bt[n][k], At[m][k], acc[ai][bj][m][n], 0, 0, 0); __builtin_amdgcn_s_setprio(0); } while (0)
; #define PG8_WAIT_V(n) asm volatile("s_waitcnt vmcnt(" #n ")" ::: "memory")
; #define PG8_WAIT_L(n) asm volatile("s_waitcnt lgkmcnt(" #n ")" ::: "memory")
; #define PG8_BAR __builtin_amdgcn_s_barrier()
; #define PG8_SCHED __builtin_amdgcn_sched_barrier(0)
; template <class Epi>
; __device__ __forceinline__ void gemm_phase(LAS unsigned char* lds, const Gemm g, const StaticOrder& S, const Epi& E) {
;     ...
;             PG8_STAGE(PG8_SB(0, 1), b2 + hstep, voffB);
;             PG8_WAIT_V(6); PG8_BAR; PG8_MMA(1, 1, At, B1); PG8_BAR;
;             PG8_LDB(B0, 1, 0); PG8_SCHED; PG8_LDA(At, 1, 0); PG8_STAGE(PG8_SA(0, 1), a2 + hstep, voffA);
;             PG8_WAIT_L(8); PG8_BAR; PG8_WAIT_L(0); PG8_MMA(0, 0, At, B0); PG8_BAR; PG8_SCHED;
;             PG8_LDB(B1, 1, 1); PG8_STAGE(PG8_SB(1, 0), b3, voffB);
;             PG8_BAR; PG8_WAIT_L(0); PG8_MMA(0, 1, At, B1); PG8_BAR;
	s_add_u32 s34, s78, 0x40000
	s_addc_u32 s35, s79, 0
	s_add_i32 vcc_hi, s96, s84
	s_mov_b32 m0, vcc_hi
	v_lshl_add_u64 v[148:149], s[34:35], 0, v[132:133]
	global_load_lds_dwordx4 v[148:149], off
	s_add_i32 m0, vcc_hi, 0x2000
	v_lshl_add_u64 v[148:149], s[34:35], 0, v[136:137]
	global_load_lds_dwordx4 v[148:149], off
	s_waitcnt vmcnt(6)
	s_barrier
	v_mfma_f32_16x16x32_f16 v[28:31], v[206:209], v[174:177], v[28:31]
	v_mfma_f32_16x16x32_f16 v[24:27], v[214:217], v[174:177], v[24:27]
	v_mfma_f32_16x16x32_f16 v[20:23], v[206:209], v[182:185], v[20:23]
	v_mfma_f32_16x16x32_f16 v[16:19], v[214:217], v[182:185], v[16:19]
	v_mfma_f32_16x16x32_f16 v[12:15], v[206:209], v[190:193], v[12:15]
	v_mfma_f32_16x16x32_f16 v[8:11], v[214:217], v[190:193], v[8:11]
	v_mfma_f32_16x16x32_f16 v[4:7], v[206:209], v[198:201], v[4:7]
	v_mfma_f32_16x16x32_f16 v[0:3], v[214:217], v[198:201], v[0:3]
	v_mfma_f32_16x16x32_f16 v[28:31], v[210:213], v[178:181], v[28:31]
	v_mfma_f32_16x16x32_f16 v[24:27], v[218:221], v[178:181], v[24:27]
	v_mfma_f32_16x16x32_f16 v[20:23], v[210:213], v[186:189], v[20:23]
	v_mfma_f32_16x16x32_f16 v[16:19], v[218:221], v[186:189], v[16:19]
	v_mfma_f32_16x16x32_f16 v[12:15], v[210:213], v[194:197], v[12:15]
	v_mfma_f32_16x16x32_f16 v[8:11], v[218:221], v[194:197], v[8:11]
	v_mfma_f32_16x16x32_f16 v[4:7], v[210:213], v[202:205], v[4:7]
	v_mfma_f32_16x16x32_f16 v[0:3], v[218:221], v[202:205], v[0:3]
	s_add_i32 vcc_hi, 0, 0x18000
	v_add_u32_e32 v138, vcc_hi, v163
	s_barrier
	ds_read_b128 v[148:151], v138
	ds_read_b128 v[152:155], v138 offset:1024
	ds_read_b128 v[156:159], v138 offset:2048
	ds_read_b128 v[170:173], v138 offset:3072
	s_add_u32 s34, s80, 0x40000
	s_addc_u32 s35, s81, 0
	s_mov_b32 m0, s87
	v_lshl_add_u64 v[206:207], s[34:35], 0, v[128:129]
	ds_read_b128 v[174:177], v166 offset:32768
	ds_read_b128 v[178:181], v166 offset:33792
	ds_read_b128 v[182:185], v166 offset:34816
	ds_read_b128 v[186:189], v166 offset:35840
	ds_read_b128 v[190:193], v166 offset:36864
	ds_read_b128 v[194:197], v166 offset:37888
	ds_read_b128 v[198:201], v166 offset:38912
	ds_read_b128 v[202:205], v166 offset:39936
	global_load_lds_dwordx4 v[206:207], off
	s_mov_b32 m0, s88
	v_lshl_add_u64 v[206:207], s[34:35], 0, v[134:135]
	global_load_lds_dwordx4 v[206:207], off
	s_waitcnt lgkmcnt(8)
	s_barrier
	s_waitcnt lgkmcnt(0)
	s_waitcnt lgkmcnt(0)
	v_mfma_f32_16x16x32_f16 v[124:127], v[148:151], v[174:177], v[124:127]
	v_mfma_f32_16x16x32_f16 v[120:123], v[156:159], v[174:177], v[120:123]
	v_mfma_f32_16x16x32_f16 v[116:119], v[148:151], v[182:185], v[116:119]
	v_mfma_f32_16x16x32_f16 v[112:115], v[156:159], v[182:185], v[112:115]
	v_mfma_f32_16x16x32_f16 v[108:111], v[148:151], v[190:193], v[108:111]
	v_mfma_f32_16x16x32_f16 v[104:107], v[156:159], v[190:193], v[104:107]
	v_mfma_f32_16x16x32_f16 v[100:103], v[148:151], v[198:201], v[100:103]
	v_mfma_f32_16x16x32_f16 v[96:99], v[156:159], v[198:201], v[96:99]
	v_mfma_f32_16x16x32_f16 v[124:127], v[152:155], v[178:181], v[124:127]
	v_mfma_f32_16x16x32_f16 v[120:123], v[170:173], v[178:181], v[120:123]
	v_mfma_f32_16x16x32_f16 v[116:119], v[152:155], v[186:189], v[116:119]
	v_mfma_f32_16x16x32_f16 v[112:115], v[170:173], v[186:189], v[112:115]
	v_mfma_f32_16x16x32_f16 v[108:111], v[152:155], v[194:197], v[108:111]
	v_mfma_f32_16x16x32_f16 v[104:107], v[170:173], v[194:197], v[104:107]
	v_mfma_f32_16x16x32_f16 v[100:103], v[152:155], v[202:205], v[100:103]
	v_mfma_f32_16x16x32_f16 v[96:99], v[170:173], v[202:205], v[96:99]
	s_barrier
	s_add_i32 s80, 0, 0x1c000
	s_add_i32 s34, vcc_hi, s84
	v_add_u32_e32 v138, s80, v163
	v_lshl_add_u64 v[160:161], v[160:161], 0, s[12:13]
	s_mov_b32 m0, s34
	ds_read_b128 v[206:209], v138
	ds_read_b128 v[210:213], v138 offset:1024
	ds_read_b128 v[214:217], v138 offset:2048
	ds_read_b128 v[218:221], v138 offset:3072
	global_load_lds_dwordx4 v[160:161], off
	s_add_i32 m0, s34, 0x2000
	v_lshl_add_u64 v[160:161], v[222:223], 0, s[12:13]
	global_load_lds_dwordx4 v[160:161], off
	s_barrier
; #define PG8_STAGE(bufoff, gbase, voff) do { _Pragma("unroll") for (int _i = 0; _i < 2; ++_i) \
;         __builtin_amdgcn_global_load_lds((const unsigned*)((const char*)(gbase) + (voff)[_i]), (LAS unsigned*)(lds + (bufoff) + ldsw + _i * 8192), 16, 0, 0); } while (0)
; #define PG8_LDA(dst, b, h) do { _Pragma("unroll") for (int m = 0; m < 4; ++m) _Pragma("unroll") for (int k = 0; k < 2; ++k) dst[m][k] = *(const LAS h16x8*)(lds + PG8_SA(b, h) + aoff + m * 2048 + k * 1024); } while (0)
; #define PG8_MMA(ai, bj, At, Bt) do { __builtin_amdgcn_s_setprio(1); _Pragma("unroll") for (int m = 0; m < 4; ++m) _Pragma("unroll") for (int n = 0; n < 2; ++n) _Pragma("unroll") for (int k = 0; k < 2; ++k) \
;         acc[ai][bj][m][n] = __builtin_amdgcn_mfma_f32_16x16x32_f16(Bt[n][k], At[m][k], acc[ai][bj][m][n], 0, 0, 0); __builtin_amdgcn_s_setprio(0); } while (0)
; #define PG8_WAIT_V(n) asm volatile("s_waitcnt vmcnt(" #n ")" ::: "memory")
; #define PG8_WAIT_L(n) asm volatile("s_waitcnt lgkmcnt(" #n ")" ::: "memory")
; #define PG8_BAR __builtin_amdgcn_s_barrier()
; #define PG8_SCHED __builtin_amdgcn_sched_barrier(0)
; template <class Epi>
; __device__ __forceinline__ void gemm_phase(LAS unsigned char* lds, const Gemm g, const StaticOrder& S, const Epi& E) {
;     ...
;             PG8_BAR; PG8_WAIT_L(0); PG8_MMA(0, 1, At, B1); PG8_BAR;
;             PG8_LDA(At, 1, 1); PG8_STAGE(PG8_SA(1, 0), a3, voffA);
;             PG8_BAR; PG8_WAIT_L(0); PG8_MMA(1, 0, At, B0); PG8_BAR; PG8_SCHED;
;             PG8_STAGE(PG8_SB(1, 1), b3 + hstep, voffB);
;             PG8_WAIT_V(6); PG8_BAR; PG8_MMA(1, 1, At, B1); PG8_BAR;
;     __device__ __forceinline__ void operator()(const f32x4 (&acc)[2][2][4][2], const pg8::Unit& u, int wr, int wc, int fr, int fq) const {
;         const int row0 = u.pm * 256 + wr * 64 + fr, col0 = u.pn * 256 + wc * 32 + 8 * fq;
; #pragma unroll
;         for (int bj = 0; bj < 2; ++bj) { const int c = col0 + bj * 128;
;             h16* base; size_t ld;
;             if (c < 3200) { base = PC + c; ld = 3200; }
;             else if (c < 4224) { base = ZCD + (c - 3200); ld = 1536; }
;             else if (c < 4736) {
	s_waitcnt lgkmcnt(0)
	s_waitcnt lgkmcnt(0)
	v_mfma_f32_16x16x32_f16 v[60:63], v[206:209], v[174:177], v[60:63]
	v_mfma_f32_16x16x32_f16 v[56:59], v[214:217], v[174:177], v[56:59]
	v_mfma_f32_16x16x32_f16 v[52:55], v[206:209], v[182:185], v[52:55]
	v_mfma_f32_16x16x32_f16 v[48:51], v[214:217], v[182:185], v[48:51]
	v_mfma_f32_16x16x32_f16 v[44:47], v[206:209], v[190:193], v[44:47]
	v_mfma_f32_16x16x32_f16 v[40:43], v[214:217], v[190:193], v[40:43]
	v_mfma_f32_16x16x32_f16 v[36:39], v[206:209], v[198:201], v[36:39]
	v_mfma_f32_16x16x32_f16 v[32:35], v[214:217], v[198:201], v[32:35]
	v_mfma_f32_16x16x32_f16 v[60:63], v[210:213], v[178:181], v[60:63]
	v_mfma_f32_16x16x32_f16 v[56:59], v[218:221], v[178:181], v[56:59]
	v_mfma_f32_16x16x32_f16 v[52:55], v[210:213], v[186:189], v[52:55]
	v_mfma_f32_16x16x32_f16 v[48:51], v[218:221], v[186:189], v[48:51]
	v_mfma_f32_16x16x32_f16 v[44:47], v[210:213], v[194:197], v[44:47]
	v_mfma_f32_16x16x32_f16 v[40:43], v[218:221], v[194:197], v[40:43]
	v_mfma_f32_16x16x32_f16 v[36:39], v[210:213], v[202:205], v[36:39]
	v_mfma_f32_16x16x32_f16 v[32:35], v[218:221], v[202:205], v[32:35]
	s_mov_b32 m0, s92
	v_lshl_add_u64 v[160:161], v[224:225], 0, s[12:13]
	s_barrier
	ds_read_b128 v[174:177], v166 offset:49152
	ds_read_b128 v[178:181], v166 offset:50176
	ds_read_b128 v[182:185], v166 offset:51200
	ds_read_b128 v[186:189], v166 offset:52224
	ds_read_b128 v[190:193], v166 offset:53248
	ds_read_b128 v[194:197], v166 offset:54272
	ds_read_b128 v[198:201], v166 offset:55296
	ds_read_b128 v[202:205], v166 offset:56320
	global_load_lds_dwordx4 v[160:161], off
	s_mov_b32 m0, s93
	v_lshl_add_u64 v[160:161], v[226:227], 0, s[12:13]
	global_load_lds_dwordx4 v[160:161], off
	s_barrier
	s_waitcnt lgkmcnt(0)
	s_waitcnt lgkmcnt(0)
	v_mfma_f32_16x16x32_f16 v[92:95], v[148:151], v[174:177], v[92:95]
	v_mfma_f32_16x16x32_f16 v[88:91], v[156:159], v[174:177], v[88:91]
	v_mfma_f32_16x16x32_f16 v[84:87], v[148:151], v[182:185], v[84:87]
	v_mfma_f32_16x16x32_f16 v[80:83], v[156:159], v[182:185], v[80:83]
	v_mfma_f32_16x16x32_f16 v[76:79], v[148:151], v[190:193], v[76:79]
	v_mfma_f32_16x16x32_f16 v[72:75], v[156:159], v[190:193], v[72:75]
	v_mfma_f32_16x16x32_f16 v[68:71], v[148:151], v[198:201], v[68:71]
	v_mfma_f32_16x16x32_f16 v[64:67], v[156:159], v[198:201], v[64:67]
	v_mfma_f32_16x16x32_f16 v[92:95], v[152:155], v[178:181], v[92:95]
	v_mfma_f32_16x16x32_f16 v[88:91], v[170:173], v[178:181], v[88:91]
	v_mfma_f32_16x16x32_f16 v[84:87], v[152:155], v[186:189], v[84:87]
	v_mfma_f32_16x16x32_f16 v[80:83], v[170:173], v[186:189], v[80:83]
	v_mfma_f32_16x16x32_f16 v[76:79], v[152:155], v[194:197], v[76:79]
	v_mfma_f32_16x16x32_f16 v[72:75], v[170:173], v[194:197], v[72:75]
	v_mfma_f32_16x16x32_f16 v[68:71], v[152:155], v[202:205], v[68:71]
	v_mfma_f32_16x16x32_f16 v[64:67], v[170:173], v[202:205], v[64:67]
	s_barrier
	s_add_u32 s34, s78, 0x40080
	s_addc_u32 s35, s79, 0
	s_add_i32 s78, s80, s84
	s_mov_b32 m0, s78
	v_lshl_add_u64 v[148:149], s[34:35], 0, v[132:133]
	global_load_lds_dwordx4 v[148:149], off
	s_add_i32 m0, s78, 0x2000
	v_lshl_add_u64 v[148:149], s[34:35], 0, v[136:137]
	global_load_lds_dwordx4 v[148:149], off
	s_waitcnt vmcnt(6)
	s_barrier
	v_mfma_f32_16x16x32_f16 v[28:31], v[206:209], v[174:177], v[28:31]
	v_mfma_f32_16x16x32_f16 v[24:27], v[214:217], v[174:177], v[24:27]
	v_mfma_f32_16x16x32_f16 v[20:23], v[206:209], v[182:185], v[20:23]
	v_mfma_f32_16x16x32_f16 v[16:19], v[214:217], v[182:185], v[16:19]
	v_mfma_f32_16x16x32_f16 v[12:15], v[206:209], v[190:193], v[12:15]
	v_mfma_f32_16x16x32_f16 v[8:11], v[214:217], v[190:193], v[8:11]
	v_mfma_f32_16x16x32_f16 v[4:7], v[206:209], v[198:201], v[4:7]
	v_mfma_f32_16x16x32_f16 v[0:3], v[214:217], v[198:201], v[0:3]
	v_mfma_f32_16x16x32_f16 v[28:31], v[210:213], v[178:181], v[28:31]
	v_mfma_f32_16x16x32_f16 v[24:27], v[218:221], v[178:181], v[24:27]
	v_mfma_f32_16x16x32_f16 v[20:23], v[210:213], v[186:189], v[20:23]
	v_mfma_f32_16x16x32_f16 v[16:19], v[218:221], v[186:189], v[16:19]
	v_mfma_f32_16x16x32_f16 v[12:15], v[210:213], v[194:197], v[12:15]
	v_mfma_f32_16x16x32_f16 v[8:11], v[218:221], v[194:197], v[8:11]
	v_mfma_f32_16x16x32_f16 v[4:7], v[210:213], v[202:205], v[4:7]
	v_mfma_f32_16x16x32_f16 v[0:3], v[218:221], v[202:205], v[0:3]
	s_add_i32 s15, s15, 2
	s_add_u32 s76, s76, 0x100
	s_addc_u32 s77, s77, 0
	s_add_u32 vcc_lo, vcc_lo, 0x100
	s_addc_u32 s14, s14, 0
	s_cmp_gt_u32 s15, 13
	s_barrier
	s_cbranch_scc0 .LBB0_485
	s_lshl_b32 s14, s54, 8
	v_or_b32_e32 v154, s14, v164
	v_lshl_add_u32 v148, s56, 8, v162
	v_cmp_lt_i32_e32 vcc, s97, v154
	s_mov_b64 s[56:57], 0
	s_and_saveexec_b64 s[34:35], vcc
	s_xor_b64 s[54:55], exec, s[34:35]
	s_cbranch_execz .LBB0_498
	s_cmpk_gt_u32 s14, 0x107f
	s_cbranch_scc0 .LBB0_491
	s_cmpk_gt_u32 s14, 0x127f
	s_cbranch_scc0 .LBB0_492
	s_mov_b64 s[76:77], 0
	s_cmpk_lt_u32 s14, 0x1480
	s_cbranch_scc0 .LBB0_493
	v_mov_b32_e32 v155, v139
	v_lshl_add_u64 v[150:151], v[154:155], 1, s[8:9]
	v_lshl_add_u64 v[158:159], v[150:151], 0, s[18:19]
	s_mov_b64 s[56:57], -1
	s_branch .LBB0_493

; #define PG8_STAGE(bufoff, gbase, voff) do { _Pragma("unroll") for (int _i = 0; _i < 2; ++_i) \
;         __builtin_amdgcn_global_load_lds((const unsigned*)((const char*)(gbase) + (voff)[_i]), (LAS unsigned*)(lds + (bufoff) + ldsw + _i * 8192), 16, 0, 0); } while (0)
; #define PG8_LDA(dst, b, h) do { _Pragma("unroll") for (int m = 0; m < 4; ++m) _Pragma("unroll") for (int k = 0; k < 2; ++k) dst[m][k] = *(const LAS h16x8*)(lds + PG8_SA(b, h) + aoff + m * 2048 + k * 1024); } while (0)
; #define PG8_LDB(dst, b, h) do { _Pragma("unroll") for (int n = 0; n < 2; ++n) _Pragma("unroll") for (int k = 0; k < 2; ++k) dst[n][k] = *(const LAS h16x8*)(lds + PG8_SB(b, h) + boff + n * 2048 + k * 1024); } while (0)
; #define PG8_MMA(ai, bj, At, Bt) do { __builtin_amdgcn_s_setprio(1); _Pragma("unroll") for (int m = 0; m < 4; ++m) _Pragma("unroll") for (int n = 0; n < 2; ++n) _Pragma("unroll") for (int k = 0; k < 2; ++k) \
;         acc[ai][bj][m][n] = __builtin_amdgcn_mfma_f32_16x16x32_f16(Bt[n][k], At[m][k], acc[ai][bj][m][n], 0, 0, 0); __builtin_amdgcn_s_setprio(0); } while (0)
; #define PG8_WAIT_V(n) asm volatile("s_waitcnt vmcnt(" #n ")" ::: "memory")
; #define PG8_WAIT_L(n) asm volatile("s_waitcnt lgkmcnt(" #n ")" ::: "memory")
; #define PG8_BAR __builtin_amdgcn_s_barrier()
; #define PG8_SCHED __builtin_amdgcn_sched_barrier(0)
; template <class Epi>
; __device__ __forceinline__ void gemm_phase(LAS unsigned char* lds, const Gemm g, const StaticOrder& S, const Epi& E) {
;     ...
;             PG8_LDB(B0, 0, 0); PG8_SCHED; PG8_LDA(At, 0, 0); PG8_STAGE(PG8_SA(1, 1), a1 + hstep, voffA);
;             PG8_WAIT_L(8); PG8_BAR; PG8_WAIT_L(0); PG8_MMA(0, 0, At, B0); PG8_BAR; PG8_SCHED;
;             PG8_LDB(B1, 0, 1); PG8_STAGE(PG8_SB(0, 0), b2, voffB);
;             PG8_BAR; PG8_WAIT_L(0); PG8_MMA(0, 1, At, B1); PG8_BAR;
;             PG8_LDA(At, 0, 1); PG8_STAGE(PG8_SA(0, 0), a2, voffA);
;             PG8_BAR; PG8_WAIT_L(0); PG8_MMA(1, 0, At, B0); PG8_BAR; PG8_SCHED;
;             PG8_STAGE(PG8_SB(0, 1), b2 + hstep, voffB);
;             PG8_WAIT_V(6); PG8_BAR; PG8_MMA(1, 1, At, B1); PG8_BAR;
.LBB0_761:
	ds_read_b128 v[152:155], v149
	ds_read_b128 v[156:159], v149 offset:1024
	ds_read_b128 v[160:163], v149 offset:2048
	ds_read_b128 v[164:167], v149 offset:3072
	s_add_u32 s28, s26, 0xfffa0080
	s_addc_u32 s29, s27, -1
	s_cmp_eq_u32 s15, 20
	s_cselect_b32 s31, s1, s29
	s_cselect_b32 s30, s0, s28
	s_cselect_b32 s29, s5, s14
	s_cselect_b32 s28, s4, s62
	v_lshl_add_u64 v[200:201], s[26:27], 0, v[138:139]
	s_add_i32 m0, s42, 0xc000
	ds_read_b128 v[168:171], v150
	ds_read_b128 v[172:175], v150 offset:1024
	ds_read_b128 v[176:179], v150 offset:2048
	ds_read_b128 v[180:183], v150 offset:3072
	ds_read_b128 v[184:187], v150 offset:4096
	ds_read_b128 v[188:191], v150 offset:5120
	ds_read_b128 v[192:195], v150 offset:6144
	ds_read_b128 v[196:199], v150 offset:7168
	global_load_lds_dwordx4 v[200:201], off
	s_add_i32 m0, s42, 0xe000
	v_lshl_add_u64 v[200:201], s[26:27], 0, v[140:141]
	global_load_lds_dwordx4 v[200:201], off
	s_waitcnt lgkmcnt(8)
	s_barrier
	s_waitcnt lgkmcnt(0)
	s_waitcnt lgkmcnt(0)
	v_mfma_f32_16x16x32_f16 v[124:127], v[152:155], v[168:171], v[124:127]
	v_mfma_f32_16x16x32_f16 v[120:123], v[160:163], v[168:171], v[120:123]
	v_mfma_f32_16x16x32_f16 v[116:119], v[152:155], v[176:179], v[116:119]
	v_mfma_f32_16x16x32_f16 v[112:115], v[160:163], v[176:179], v[112:115]
	v_mfma_f32_16x16x32_f16 v[100:103], v[152:155], v[184:187], v[100:103]
	v_mfma_f32_16x16x32_f16 v[96:99], v[160:163], v[184:187], v[96:99]
	v_mfma_f32_16x16x32_f16 v[84:87], v[152:155], v[192:195], v[84:87]
	v_mfma_f32_16x16x32_f16 v[80:83], v[160:163], v[192:195], v[80:83]
	v_mfma_f32_16x16x32_f16 v[124:127], v[156:159], v[172:175], v[124:127]
	v_mfma_f32_16x16x32_f16 v[120:123], v[164:167], v[172:175], v[120:123]
	v_mfma_f32_16x16x32_f16 v[116:119], v[156:159], v[180:183], v[116:119]
	v_mfma_f32_16x16x32_f16 v[112:115], v[164:167], v[180:183], v[112:115]
	v_mfma_f32_16x16x32_f16 v[100:103], v[156:159], v[188:191], v[100:103]
	v_mfma_f32_16x16x32_f16 v[96:99], v[164:167], v[188:191], v[96:99]
	v_mfma_f32_16x16x32_f16 v[84:87], v[156:159], v[196:199], v[84:87]
	v_mfma_f32_16x16x32_f16 v[80:83], v[164:167], v[196:199], v[80:83]
	s_barrier
	s_add_i32 s34, s53, s40
	v_lshl_add_u64 v[216:217], s[28:29], 0, v[132:133]
	s_mov_b32 m0, s34
	ds_read_b128 v[200:203], v151
	ds_read_b128 v[204:207], v151 offset:1024
	ds_read_b128 v[208:211], v151 offset:2048
	ds_read_b128 v[212:215], v151 offset:3072
	global_load_lds_dwordx4 v[216:217], off
	s_add_i32 m0, s34, 0x2000
	v_lshl_add_u64 v[218:219], s[28:29], 0, v[136:137]
	global_load_lds_dwordx4 v[218:219], off
	s_barrier
	s_waitcnt lgkmcnt(0)
	s_waitcnt lgkmcnt(0)
	v_mfma_f32_16x16x32_f16 v[108:111], v[200:203], v[168:171], v[108:111]
	v_mfma_f32_16x16x32_f16 v[104:107], v[208:211], v[168:171], v[104:107]
	v_mfma_f32_16x16x32_f16 v[92:95], v[200:203], v[176:179], v[92:95]
	v_mfma_f32_16x16x32_f16 v[88:91], v[208:211], v[176:179], v[88:91]
	v_mfma_f32_16x16x32_f16 v[76:79], v[200:203], v[184:187], v[76:79]
	v_mfma_f32_16x16x32_f16 v[72:75], v[208:211], v[184:187], v[72:75]
	v_mfma_f32_16x16x32_f16 v[68:71], v[200:203], v[192:195], v[68:71]
	v_mfma_f32_16x16x32_f16 v[64:67], v[208:211], v[192:195], v[64:67]
	v_mfma_f32_16x16x32_f16 v[108:111], v[204:207], v[172:175], v[108:111]
	v_mfma_f32_16x16x32_f16 v[104:107], v[212:215], v[172:175], v[104:107]
	v_mfma_f32_16x16x32_f16 v[92:95], v[204:207], v[180:183], v[92:95]
	v_mfma_f32_16x16x32_f16 v[88:91], v[212:215], v[180:183], v[88:91]
	v_mfma_f32_16x16x32_f16 v[76:79], v[204:207], v[188:191], v[76:79]
	v_mfma_f32_16x16x32_f16 v[72:75], v[212:215], v[188:191], v[72:75]
	v_mfma_f32_16x16x32_f16 v[68:71], v[204:207], v[196:199], v[68:71]
	v_mfma_f32_16x16x32_f16 v[64:67], v[212:215], v[196:199], v[64:67]
	s_mov_b32 m0, s42
	v_lshl_add_u64 v[220:221], s[30:31], 0, v[128:129]
	s_barrier
	ds_read_b128 v[168:171], v150 offset:16384
	ds_read_b128 v[172:175], v150 offset:17408
	ds_read_b128 v[176:179], v150 offset:18432
	ds_read_b128 v[180:183], v150 offset:19456
	ds_read_b128 v[184:187], v150 offset:20480
	ds_read_b128 v[188:191], v150 offset:21504
	ds_read_b128 v[192:195], v150 offset:22528
	ds_read_b128 v[196:199], v150 offset:23552
	global_load_lds_dwordx4 v[220:221], off
	s_mov_b32 m0, s43
	v_lshl_add_u64 v[222:223], s[30:31], 0, v[134:135]
	global_load_lds_dwordx4 v[222:223], off
	s_barrier
	s_waitcnt lgkmcnt(0)
	s_waitcnt lgkmcnt(0)
	v_mfma_f32_16x16x32_f16 v[60:63], v[152:155], v[168:171], v[60:63]
	v_mfma_f32_16x16x32_f16 v[56:59], v[160:163], v[168:171], v[56:59]
	v_mfma_f32_16x16x32_f16 v[52:55], v[152:155], v[176:179], v[52:55]
	v_mfma_f32_16x16x32_f16 v[48:51], v[160:163], v[176:179], v[48:51]
	v_mfma_f32_16x16x32_f16 v[36:39], v[152:155], v[184:187], v[36:39]
	v_mfma_f32_16x16x32_f16 v[32:35], v[160:163], v[184:187], v[32:35]
	v_mfma_f32_16x16x32_f16 v[20:23], v[152:155], v[192:195], v[20:23]
	v_mfma_f32_16x16x32_f16 v[16:19], v[160:163], v[192:195], v[16:19]
	v_mfma_f32_16x16x32_f16 v[60:63], v[156:159], v[172:175], v[60:63]
	v_mfma_f32_16x16x32_f16 v[56:59], v[164:167], v[172:175], v[56:59]
	v_mfma_f32_16x16x32_f16 v[52:55], v[156:159], v[180:183], v[52:55]
	v_mfma_f32_16x16x32_f16 v[48:51], v[164:167], v[180:183], v[48:51]
	v_mfma_f32_16x16x32_f16 v[36:39], v[156:159], v[188:191], v[36:39]
	v_mfma_f32_16x16x32_f16 v[32:35], v[164:167], v[188:191], v[32:35]
	v_mfma_f32_16x16x32_f16 v[20:23], v[156:159], v[196:199], v[20:23]
	v_mfma_f32_16x16x32_f16 v[16:19], v[164:167], v[196:199], v[16:19]
	s_barrier
	s_add_u32 s34, s28, 0x60000
	s_addc_u32 s35, s29, 0
	s_add_i32 s63, s54, s40
	s_mov_b32 m0, s63
	v_lshl_add_u64 v[152:153], s[34:35], 0, v[132:133]
	global_load_lds_dwordx4 v[152:153], off
	s_add_i32 m0, s63, 0x2000
	v_lshl_add_u64 v[152:153], s[34:35], 0, v[136:137]
	global_load_lds_dwordx4 v[152:153], off
	s_waitcnt vmcnt(6)
	s_barrier
; #define PG8_STAGE(bufoff, gbase, voff) do { _Pragma("unroll") for (int _i = 0; _i < 2; ++_i) \
;         __builtin_amdgcn_global_load_lds((const unsigned*)((const char*)(gbase) + (voff)[_i]), (LAS unsigned*)(lds + (bufoff) + ldsw + _i * 8192), 16, 0, 0); } while (0)
; #define PG8_LDA(dst, b, h) do { _Pragma("unroll") for (int m = 0; m < 4; ++m) _Pragma("unroll") for (int k = 0; k < 2; ++k) dst[m][k] = *(const LAS h16x8*)(lds + PG8_SA(b, h) + aoff + m * 2048 + k * 1024); } while (0)
; #define PG8_LDB(dst, b, h) do { _Pragma("unroll") for (int n = 0; n < 2; ++n) _Pragma("unroll") for (int k = 0; k < 2; ++k) dst[n][k] = *(const LAS h16x8*)(lds + PG8_SB(b, h) + boff + n * 2048 + k * 1024); } while (0)
; #define PG8_MMA(ai, bj, At, Bt) do { __builtin_amdgcn_s_setprio(1); _Pragma("unroll") for (int m = 0; m < 4; ++m) _Pragma("unroll") for (int n = 0; n < 2; ++n) _Pragma("unroll") for (int k = 0; k < 2; ++k) \
;         acc[ai][bj][m][n] = __builtin_amdgcn_mfma_f32_16x16x32_f16(Bt[n][k], At[m][k], acc[ai][bj][m][n], 0, 0, 0); __builtin_amdgcn_s_setprio(0); } while (0)
; #define PG8_WAIT_V(n) asm volatile("s_waitcnt vmcnt(" #n ")" ::: "memory")
; #define PG8_WAIT_L(n) asm volatile("s_waitcnt lgkmcnt(" #n ")" ::: "memory")
; #define PG8_BAR __builtin_amdgcn_s_barrier()
; #define PG8_SCHED __builtin_amdgcn_sched_barrier(0)
; template <class Epi>
; __device__ __forceinline__ void gemm_phase(LAS unsigned char* lds, const Gemm g, const StaticOrder& S, const Epi& E) {
;     ...
;             PG8_WAIT_V(6); PG8_BAR; PG8_MMA(1, 1, At, B1); PG8_BAR;
;             PG8_LDB(B0, 1, 0); PG8_SCHED; PG8_LDA(At, 1, 0); PG8_STAGE(PG8_SA(0, 1), a2 + hstep, voffA);
;             PG8_WAIT_L(8); PG8_BAR; PG8_WAIT_L(0); PG8_MMA(0, 0, At, B0); PG8_BAR; PG8_SCHED;
;             PG8_LDB(B1, 1, 1); PG8_STAGE(PG8_SB(1, 0), b3, voffB);
;             PG8_BAR; PG8_WAIT_L(0); PG8_MMA(0, 1, At, B1); PG8_BAR;
;             PG8_LDA(At, 1, 1); PG8_STAGE(PG8_SA(1, 0), a3, voffA);
;             PG8_BAR; PG8_WAIT_L(0); PG8_MMA(1, 0, At, B0); PG8_BAR; PG8_SCHED;
	v_mfma_f32_16x16x32_f16 v[44:47], v[200:203], v[168:171], v[44:47]
	v_mfma_f32_16x16x32_f16 v[40:43], v[208:211], v[168:171], v[40:43]
	v_mfma_f32_16x16x32_f16 v[28:31], v[200:203], v[176:179], v[28:31]
	v_mfma_f32_16x16x32_f16 v[24:27], v[208:211], v[176:179], v[24:27]
	v_mfma_f32_16x16x32_f16 v[12:15], v[200:203], v[184:187], v[12:15]
	v_mfma_f32_16x16x32_f16 v[8:11], v[208:211], v[184:187], v[8:11]
	v_mfma_f32_16x16x32_f16 v[4:7], v[200:203], v[192:195], v[4:7]
	v_mfma_f32_16x16x32_f16 v[0:3], v[208:211], v[192:195], v[0:3]
	v_mfma_f32_16x16x32_f16 v[44:47], v[204:207], v[172:175], v[44:47]
	v_mfma_f32_16x16x32_f16 v[40:43], v[212:215], v[172:175], v[40:43]
	v_mfma_f32_16x16x32_f16 v[28:31], v[204:207], v[180:183], v[28:31]
	v_mfma_f32_16x16x32_f16 v[24:27], v[212:215], v[180:183], v[24:27]
	v_mfma_f32_16x16x32_f16 v[12:15], v[204:207], v[188:191], v[12:15]
	v_mfma_f32_16x16x32_f16 v[8:11], v[212:215], v[188:191], v[8:11]
	v_mfma_f32_16x16x32_f16 v[4:7], v[204:207], v[196:199], v[4:7]
	v_mfma_f32_16x16x32_f16 v[0:3], v[212:215], v[196:199], v[0:3]
	s_add_i32 s34, 0, 0x18000
	v_add_u32_e32 v164, s34, v147
	s_barrier
	ds_read_b128 v[152:155], v164
	ds_read_b128 v[156:159], v164 offset:1024
	ds_read_b128 v[160:163], v164 offset:2048
	ds_read_b128 v[164:167], v164 offset:3072
	s_add_u32 s30, s30, 0x60000
	s_addc_u32 s31, s31, 0
	s_mov_b32 m0, s44
	v_lshl_add_u64 v[200:201], s[30:31], 0, v[128:129]
	ds_read_b128 v[168:171], v150 offset:32768
	ds_read_b128 v[172:175], v150 offset:33792
	ds_read_b128 v[176:179], v150 offset:34816
	ds_read_b128 v[180:183], v150 offset:35840
	ds_read_b128 v[184:187], v150 offset:36864
	ds_read_b128 v[188:191], v150 offset:37888
	ds_read_b128 v[192:195], v150 offset:38912
	ds_read_b128 v[196:199], v150 offset:39936
	global_load_lds_dwordx4 v[200:201], off
	s_mov_b32 m0, s45
	v_lshl_add_u64 v[200:201], s[30:31], 0, v[134:135]
	global_load_lds_dwordx4 v[200:201], off
	s_waitcnt lgkmcnt(8)
	s_barrier
	s_waitcnt lgkmcnt(0)
	s_waitcnt lgkmcnt(0)
	v_mfma_f32_16x16x32_f16 v[124:127], v[152:155], v[168:171], v[124:127]
	v_mfma_f32_16x16x32_f16 v[120:123], v[160:163], v[168:171], v[120:123]
	v_mfma_f32_16x16x32_f16 v[116:119], v[152:155], v[176:179], v[116:119]
	v_mfma_f32_16x16x32_f16 v[112:115], v[160:163], v[176:179], v[112:115]
	v_mfma_f32_16x16x32_f16 v[100:103], v[152:155], v[184:187], v[100:103]
	v_mfma_f32_16x16x32_f16 v[96:99], v[160:163], v[184:187], v[96:99]
	v_mfma_f32_16x16x32_f16 v[84:87], v[152:155], v[192:195], v[84:87]
	v_mfma_f32_16x16x32_f16 v[80:83], v[160:163], v[192:195], v[80:83]
	v_mfma_f32_16x16x32_f16 v[124:127], v[156:159], v[172:175], v[124:127]
	v_mfma_f32_16x16x32_f16 v[120:123], v[164:167], v[172:175], v[120:123]
	v_mfma_f32_16x16x32_f16 v[116:119], v[156:159], v[180:183], v[116:119]
	v_mfma_f32_16x16x32_f16 v[112:115], v[164:167], v[180:183], v[112:115]
	v_mfma_f32_16x16x32_f16 v[100:103], v[156:159], v[188:191], v[100:103]
	v_mfma_f32_16x16x32_f16 v[96:99], v[164:167], v[188:191], v[96:99]
	v_mfma_f32_16x16x32_f16 v[84:87], v[156:159], v[196:199], v[84:87]
	v_mfma_f32_16x16x32_f16 v[80:83], v[164:167], v[196:199], v[80:83]
	s_barrier
	s_add_i32 s30, 0, 0x1c000
	s_add_i32 s31, s34, s40
	v_add_u32_e32 v212, s30, v147
	v_lshl_add_u64 v[216:217], v[216:217], 0, s[12:13]
	s_mov_b32 m0, s31
	ds_read_b128 v[200:203], v212
	ds_read_b128 v[204:207], v212 offset:1024
	ds_read_b128 v[208:211], v212 offset:2048
	ds_read_b128 v[212:215], v212 offset:3072
	global_load_lds_dwordx4 v[216:217], off
	s_add_i32 m0, s31, 0x2000
	v_lshl_add_u64 v[216:217], v[218:219], 0, s[12:13]
	global_load_lds_dwordx4 v[216:217], off
	s_barrier
	s_waitcnt lgkmcnt(0)
	s_waitcnt lgkmcnt(0)
	v_mfma_f32_16x16x32_f16 v[108:111], v[200:203], v[168:171], v[108:111]
	v_mfma_f32_16x16x32_f16 v[104:107], v[208:211], v[168:171], v[104:107]
	v_mfma_f32_16x16x32_f16 v[92:95], v[200:203], v[176:179], v[92:95]
	v_mfma_f32_16x16x32_f16 v[88:91], v[208:211], v[176:179], v[88:91]
	v_mfma_f32_16x16x32_f16 v[76:79], v[200:203], v[184:187], v[76:79]
	v_mfma_f32_16x16x32_f16 v[72:75], v[208:211], v[184:187], v[72:75]
	v_mfma_f32_16x16x32_f16 v[68:71], v[200:203], v[192:195], v[68:71]
	v_mfma_f32_16x16x32_f16 v[64:67], v[208:211], v[192:195], v[64:67]
	v_mfma_f32_16x16x32_f16 v[108:111], v[204:207], v[172:175], v[108:111]
	v_mfma_f32_16x16x32_f16 v[104:107], v[212:215], v[172:175], v[104:107]
	v_mfma_f32_16x16x32_f16 v[92:95], v[204:207], v[180:183], v[92:95]
	v_mfma_f32_16x16x32_f16 v[88:91], v[212:215], v[180:183], v[88:91]
	v_mfma_f32_16x16x32_f16 v[76:79], v[204:207], v[188:191], v[76:79]
	v_mfma_f32_16x16x32_f16 v[72:75], v[212:215], v[188:191], v[72:75]
	v_mfma_f32_16x16x32_f16 v[68:71], v[204:207], v[196:199], v[68:71]
	v_mfma_f32_16x16x32_f16 v[64:67], v[212:215], v[196:199], v[64:67]
	s_mov_b32 m0, s48
	v_lshl_add_u64 v[216:217], v[220:221], 0, s[12:13]
	s_barrier
	ds_read_b128 v[168:171], v150 offset:49152
	ds_read_b128 v[172:175], v150 offset:50176
	ds_read_b128 v[176:179], v150 offset:51200
	ds_read_b128 v[180:183], v150 offset:52224
	ds_read_b128 v[184:187], v150 offset:53248
	ds_read_b128 v[188:191], v150 offset:54272
	ds_read_b128 v[192:195], v150 offset:55296
	ds_read_b128 v[196:199], v150 offset:56320
	global_load_lds_dwordx4 v[216:217], off
	s_mov_b32 m0, s49
	v_lshl_add_u64 v[216:217], v[222:223], 0, s[12:13]
	global_load_lds_dwordx4 v[216:217], off
	s_barrier
; #define PG8_STAGE(bufoff, gbase, voff) do { _Pragma("unroll") for (int _i = 0; _i < 2; ++_i) \
;         __builtin_amdgcn_global_load_lds((const unsigned*)((const char*)(gbase) + (voff)[_i]), (LAS unsigned*)(lds + (bufoff) + ldsw + _i * 8192), 16, 0, 0); } while (0)
; #define PG8_MMA(ai, bj, At, Bt) do { __builtin_amdgcn_s_setprio(1); _Pragma("unroll") for (int m = 0; m < 4; ++m) _Pragma("unroll") for (int n = 0; n < 2; ++n) _Pragma("unroll") for (int k = 0; k < 2; ++k) \
;         acc[ai][bj][m][n] = __builtin_amdgcn_mfma_f32_16x16x32_f16(Bt[n][k], At[m][k], acc[ai][bj][m][n], 0, 0, 0); __builtin_amdgcn_s_setprio(0); } while (0)
; #define PG8_WAIT_V(n) asm volatile("s_waitcnt vmcnt(" #n ")" ::: "memory")
; #define PG8_WAIT_L(n) asm volatile("s_waitcnt lgkmcnt(" #n ")" ::: "memory")
; #define PG8_BAR __builtin_amdgcn_s_barrier()
; #define PG8_SCHED __builtin_amdgcn_sched_barrier(0)
; template <class Epi>
; __device__ __forceinline__ void gemm_phase(LAS unsigned char* lds, const Gemm g, const StaticOrder& S, const Epi& E) {
;     ...
;             PG8_BAR; PG8_WAIT_L(0); PG8_MMA(1, 0, At, B0); PG8_BAR; PG8_SCHED;
;             PG8_STAGE(PG8_SB(1, 1), b3 + hstep, voffB);
;             PG8_WAIT_V(6); PG8_BAR; PG8_MMA(1, 1, At, B1); PG8_BAR;
	s_waitcnt lgkmcnt(0)
	s_waitcnt lgkmcnt(0)
	v_mfma_f32_16x16x32_f16 v[60:63], v[152:155], v[168:171], v[60:63]
	v_mfma_f32_16x16x32_f16 v[56:59], v[160:163], v[168:171], v[56:59]
	v_mfma_f32_16x16x32_f16 v[52:55], v[152:155], v[176:179], v[52:55]
	v_mfma_f32_16x16x32_f16 v[48:51], v[160:163], v[176:179], v[48:51]
	v_mfma_f32_16x16x32_f16 v[36:39], v[152:155], v[184:187], v[36:39]
	v_mfma_f32_16x16x32_f16 v[32:35], v[160:163], v[184:187], v[32:35]
	v_mfma_f32_16x16x32_f16 v[20:23], v[152:155], v[192:195], v[20:23]
	v_mfma_f32_16x16x32_f16 v[16:19], v[160:163], v[192:195], v[16:19]
	v_mfma_f32_16x16x32_f16 v[60:63], v[156:159], v[172:175], v[60:63]
	v_mfma_f32_16x16x32_f16 v[56:59], v[164:167], v[172:175], v[56:59]
	v_mfma_f32_16x16x32_f16 v[52:55], v[156:159], v[180:183], v[52:55]
	v_mfma_f32_16x16x32_f16 v[48:51], v[164:167], v[180:183], v[48:51]
	v_mfma_f32_16x16x32_f16 v[36:39], v[156:159], v[188:191], v[36:39]
	v_mfma_f32_16x16x32_f16 v[32:35], v[164:167], v[188:191], v[32:35]
	v_mfma_f32_16x16x32_f16 v[20:23], v[156:159], v[196:199], v[20:23]
	v_mfma_f32_16x16x32_f16 v[16:19], v[164:167], v[196:199], v[16:19]
	s_barrier
	s_add_u32 s28, s28, 0x60080
	s_addc_u32 s29, s29, 0
	s_add_i32 s30, s30, s40
	s_mov_b32 m0, s30
	v_lshl_add_u64 v[152:153], s[28:29], 0, v[132:133]
	global_load_lds_dwordx4 v[152:153], off
	s_add_i32 m0, s30, 0x2000
	v_lshl_add_u64 v[152:153], s[28:29], 0, v[136:137]
	global_load_lds_dwordx4 v[152:153], off
	s_waitcnt vmcnt(6)
	s_barrier
	v_mfma_f32_16x16x32_f16 v[44:47], v[200:203], v[168:171], v[44:47]
	v_mfma_f32_16x16x32_f16 v[40:43], v[208:211], v[168:171], v[40:43]
	v_mfma_f32_16x16x32_f16 v[28:31], v[200:203], v[176:179], v[28:31]
	v_mfma_f32_16x16x32_f16 v[24:27], v[208:211], v[176:179], v[24:27]
	v_mfma_f32_16x16x32_f16 v[12:15], v[200:203], v[184:187], v[12:15]
	v_mfma_f32_16x16x32_f16 v[8:11], v[208:211], v[184:187], v[8:11]
	v_mfma_f32_16x16x32_f16 v[4:7], v[200:203], v[192:195], v[4:7]
	v_mfma_f32_16x16x32_f16 v[0:3], v[208:211], v[192:195], v[0:3]
	v_mfma_f32_16x16x32_f16 v[44:47], v[204:207], v[172:175], v[44:47]
	v_mfma_f32_16x16x32_f16 v[40:43], v[212:215], v[172:175], v[40:43]
	v_mfma_f32_16x16x32_f16 v[28:31], v[204:207], v[180:183], v[28:31]
	v_mfma_f32_16x16x32_f16 v[24:27], v[212:215], v[180:183], v[24:27]
	v_mfma_f32_16x16x32_f16 v[12:15], v[204:207], v[188:191], v[12:15]
	v_mfma_f32_16x16x32_f16 v[8:11], v[212:215], v[188:191], v[8:11]
	v_mfma_f32_16x16x32_f16 v[4:7], v[204:207], v[196:199], v[4:7]
	v_mfma_f32_16x16x32_f16 v[0:3], v[212:215], v[196:199], v[0:3]
	s_add_i32 s15, s15, 2
	s_add_u32 s26, s26, 0x100
	s_addc_u32 s27, s27, 0
	s_add_u32 s62, s62, 0x100
	s_addc_u32 s14, s14, 0
	s_cmp_gt_u32 s15, 21
	s_barrier
	s_cbranch_scc0 .LBB0_761
; #define PG8_WAIT_V(n) asm volatile("s_waitcnt vmcnt(" #n ")" ::: "memory")
; #define PG8_BAR __builtin_amdgcn_s_barrier()
; template <class Epi>
; __device__ __forceinline__ void gemm_phase(LAS unsigned char* lds, const Gemm g, const StaticOrder& S, const Epi& E) {
;     ...
;         cur = nxt; cA = nA; cB = nB; ++ui;
;     }
;     PG8_WAIT_V(0);
;     if (wr == 0) PG8_BAR;
;     __device__ __forceinline__ void operator()(const f32x4 (&acc)[2][2][4][2], const pg8::Unit& u, int wr, int wc, int fr, int fq) const {
;         const int row0 = u.pm * 256 + wr * 64 + fr, col0 = u.pn * 256 + wc * 32 + 8 * fq;
; #pragma unroll
;         for (int ai = 0; ai < 2; ++ai)
; #pragma unroll
;             for (int m = 0; m < 4; ++m) { const size_t r = (size_t)(row0 + ai * 128 + m * 16);
; #pragma unroll
;                 for (int bj = 0; bj < 2; ++bj) { const f32x4 v0 = acc[ai][bj][m][0], v1 = acc[ai][bj][m][1]; h16x8 o;
; #pragma unroll
;                     for (int e = 0; e < 4; ++e) { o[e] = (h16)v0[e]; o[4 + e] = (h16)v1[e]; }
;                     *(h16x8*)(O2 + r * 1024 + col0 + bj * 128) = o; } }
	v_lshl_add_u32 v152, s58, 8, v146
	v_lshl_or_b32 v154, s61, 8, v148
	v_ashrrev_i32_e32 v153, 31, v152
	v_ashrrev_i32_e32 v155, 31, v154
	v_lshlrev_b64 v[156:157], 11, v[152:153]
	v_cvt_pk_f16_f32 v123, v122, v123
	v_cvt_pk_f16_f32 v122, v120, v121
	v_cvt_pk_f16_f32 v121, v126, v127
	v_cvt_pk_f16_f32 v120, v124, v125
	v_lshl_add_u64 v[124:125], s[10:11], 0, v[156:157]
	v_lshlrev_b64 v[126:127], 1, v[154:155]
	v_lshl_add_u64 v[124:125], v[124:125], 0, v[126:127]
	v_cvt_pk_f16_f32 v107, v106, v107
	v_cvt_pk_f16_f32 v106, v104, v105
	v_cvt_pk_f16_f32 v105, v110, v111
	v_cvt_pk_f16_f32 v104, v108, v109
	global_store_dwordx4 v[124:125], v[104:107], off offset:256
	v_cvt_pk_f16_f32 v91, v90, v91
	v_cvt_pk_f16_f32 v90, v88, v89
	v_or_b32_e32 v104, 16, v152
	v_ashrrev_i32_e32 v105, 31, v104
	v_lshlrev_b64 v[108:109], 11, v[104:105]
	v_lshl_add_u64 v[108:109], s[10:11], 0, v[108:109]
	v_lshl_add_u64 v[108:109], v[108:109], 0, v[126:127]
	v_cvt_pk_f16_f32 v89, v94, v95
	v_cvt_pk_f16_f32 v88, v92, v93
	global_store_dwordx4 v[108:109], v[88:91], off offset:256
	v_cvt_pk_f16_f32 v59, v58, v59
	v_cvt_pk_f16_f32 v58, v56, v57
	v_or_b32_e32 v88, 32, v152
	v_ashrrev_i32_e32 v89, 31, v88
	v_cvt_pk_f16_f32 v57, v62, v63
	v_add_co_u32_e32 v62, vcc, s55, v124
	v_lshlrev_b64 v[92:93], 11, v[88:89]
	s_nop 0
	v_addc_co_u32_e32 v63, vcc, 0, v125, vcc
	v_lshl_add_u64 v[92:93], s[10:11], 0, v[92:93]
	v_cvt_pk_f16_f32 v43, v42, v43
	v_cvt_pk_f16_f32 v42, v40, v41
	v_cvt_pk_f16_f32 v41, v46, v47
	v_add_co_u32_e32 v46, vcc, s56, v124
	v_lshl_add_u64 v[92:93], v[92:93], 0, v[126:127]
	v_cvt_pk_f16_f32 v75, v74, v75
	v_cvt_pk_f16_f32 v74, v72, v73
	v_cvt_pk_f16_f32 v73, v78, v79
	v_cvt_pk_f16_f32 v72, v76, v77
	v_addc_co_u32_e32 v47, vcc, 0, v125, vcc
	global_store_dwordx4 v[92:93], v[72:75], off offset:256
	v_cvt_pk_f16_f32 v27, v26, v27
	v_cvt_pk_f16_f32 v26, v24, v25
	v_or_b32_e32 v72, 48, v152
	v_cvt_pk_f16_f32 v25, v30, v31
	v_add_co_u32_e32 v30, vcc, s57, v124
	v_ashrrev_i32_e32 v73, 31, v72
	s_nop 0
	v_addc_co_u32_e32 v31, vcc, 0, v125, vcc
	v_lshlrev_b64 v[76:77], 11, v[72:73]
	v_cvt_pk_f16_f32 v11, v10, v11
	v_cvt_pk_f16_f32 v10, v8, v9
	v_cvt_pk_f16_f32 v9, v14, v15
	v_add_co_u32_e32 v14, vcc, 0x58000, v124
	v_lshl_add_u64 v[76:77], s[10:11], 0, v[76:77]
	v_cvt_pk_f16_f32 v56, v60, v61
	v_lshl_add_u64 v[60:61], v[124:125], 0, s[18:19]
	v_cvt_pk_f16_f32 v40, v44, v45
	v_lshl_add_u64 v[44:45], v[124:125], 0, s[20:21]
	v_cvt_pk_f16_f32 v24, v28, v29
	v_lshl_add_u64 v[28:29], v[124:125], 0, s[22:23]
	v_cvt_pk_f16_f32 v8, v12, v13
	v_addc_co_u32_e32 v15, vcc, 0, v125, vcc
	v_cvt_pk_f16_f32 v107, v114, v115
	v_cvt_pk_f16_f32 v106, v112, v113
	v_cvt_pk_f16_f32 v105, v118, v119
	v_cvt_pk_f16_f32 v104, v116, v117
	v_cvt_pk_f16_f32 v91, v98, v99
	v_cvt_pk_f16_f32 v90, v96, v97
	v_cvt_pk_f16_f32 v89, v102, v103
	v_cvt_pk_f16_f32 v88, v100, v101
	v_cvt_pk_f16_f32 v75, v82, v83
	v_cvt_pk_f16_f32 v74, v80, v81
	v_cvt_pk_f16_f32 v73, v86, v87
	v_cvt_pk_f16_f32 v72, v84, v85
	v_lshl_add_u64 v[76:77], v[76:77], 0, v[126:127]
	v_cvt_pk_f16_f32 v67, v66, v67
	v_cvt_pk_f16_f32 v66, v64, v65
	v_cvt_pk_f16_f32 v65, v70, v71
	v_cvt_pk_f16_f32 v64, v68, v69
	global_store_dwordx4 v[60:61], v[40:43], off offset:256
	global_store_dwordx4 v[44:45], v[24:27], off offset:256
	global_store_dwordx4 v[28:29], v[8:11], off offset:256
	v_cvt_pk_f16_f32 v43, v50, v51
	v_cvt_pk_f16_f32 v42, v48, v49
	v_cvt_pk_f16_f32 v41, v54, v55
	v_cvt_pk_f16_f32 v40, v52, v53
	v_cvt_pk_f16_f32 v27, v34, v35
	v_cvt_pk_f16_f32 v26, v32, v33
	v_cvt_pk_f16_f32 v25, v38, v39
	v_cvt_pk_f16_f32 v24, v36, v37
	v_cvt_pk_f16_f32 v11, v18, v19
	v_cvt_pk_f16_f32 v10, v16, v17
	v_cvt_pk_f16_f32 v9, v22, v23
	v_cvt_pk_f16_f32 v8, v20, v21
	v_lshl_add_u64 v[12:13], v[124:125], 0, s[24:25]
	v_cvt_pk_f16_f32 v3, v2, v3
	v_cvt_pk_f16_f32 v2, v0, v1
	v_cvt_pk_f16_f32 v1, v6, v7
	v_cvt_pk_f16_f32 v0, v4, v5
	s_and_b64 vcc, exec, s[6:7]
	s_mov_b32 s61, s59
	s_mov_b32 s58, s60
	s_mov_b64 s[28:29], s[4:5]
	s_mov_b64 s[26:27], s[0:1]
	global_store_dwordx4 v[124:125], v[120:123], off
	global_store_dwordx4 v[108:109], v[104:107], off
	global_store_dwordx4 v[92:93], v[88:91], off
	global_store_dwordx4 v[76:77], v[72:75], off
	global_store_dwordx4 v[76:77], v[64:67], off offset:256
	global_store_dwordx4 v[62:63], v[56:59], off
	global_store_dwordx4 v[46:47], v[40:43], off
	global_store_dwordx4 v[30:31], v[24:27], off
	global_store_dwordx4 v[14:15], v[8:11], off
	global_store_dwordx4 v[12:13], v[0:3], off offset:256
	s_cbranch_vccz .LBB0_750
	s_waitcnt vmcnt(0)
	s_cmpk_gt_u32 s33, 0xff
	s_cbranch_scc1 .LBB0_765
	s_barrier
